# scan y pass diagonal block: validity mask via one compare + SALU mask algebra instead of two compares, three cndmask, and, compare (60 elements), filler nops removed
# speedup vs baseline: 1.0036x; 1.0036x over previous
; #define LAS __attribute__((address_space(3)))
; template <int MODE> __device__ __forceinline__ void ssd_scan_phase(Frame& F, int j, bool ctx_out) {
;     ...
;             if (need_y && !(MODE & 1)) {
;                 bf16x8 hf[2][4];
; #pragma unroll
;                 for (int pt = 0; pt < 2; ++pt)
; #pragma unroll
;                     for (int q = 0; q < 4; ++q) { const f32x4 lo4 = hT[2 * q][pt], hi4 = hT[2 * q + 1][pt]; u32x4 o; o.x = cvt_pk_bf16(lo4[0], lo4[1]); o.y = cvt_pk_bf16(lo4[2], lo4[3]); o.z = cvt_pk_bf16(hi4[0], hi4[1]); o.w = cvt_pk_bf16(hi4[2], hi4[3]);
;                         hf[pt][q] = __builtin_bit_cast(bf16x8, o); }
;                 bf16x8 xb_cur = xf[1][0], xb_nxt = xf[1][0];
; #pragma unroll 8
;                 for (int lt = 0; lt < 8; ++lt) {
;                     const int l = 16 * lt + fr; const float cl = tab[l];
;                     f32x4 accd[2], acco[2];
;                     accd[0] = accd[1] = acco[0] = acco[1] = (f32x4){0.f, 0.f, 0.f, 0.f};
;                     const int kd = lt >> 1;
;                     if ((lt & 1) == 0) { xb_cur = xb_nxt; if (kd + 1 < 4) xb_nxt = *(const bf16x8*)(xl + (size_t)16 * T + 32 * (kd + 1)); }
;                     const bf16x8 xa = xf[0][kd], xb = xb_cur;
; #pragma unroll
;                     for (int ks = 0; ks < 4; ++ks) {
;                         const bool full = dir == 0 ? (ks < kd) : (ks > kd);
;                         if (full) {
;                             const bf16x8 gf = *(const LAS bf16x8*)(GS + l * 256 + (((4 * ks + fq) ^ fr) << 4));
;                             const float f1 = __builtin_amdgcn_exp2f(cl - tab[dir == 0 ? 32 * ks + 31 : 32 * ks]);
;                             const f32x4 z4 = (f32x4){0.f, 0.f, 0.f, 0.f};
;                             const f32x4 t0 = __builtin_amdgcn_mfma_f32_16x16x32_bf16(xs2[0][ks], gf, z4, 0, 0, 0), t1 = __builtin_amdgcn_mfma_f32_16x16x32_bf16(xs2[1][ks], gf, z4, 0, 0, 0);
;                             accd[0] += t0 * f1; accd[1] += t1 * f1;
;                         }
;                     }
; #pragma unroll
;                     for (int q = 0; q < 4; ++q) {
;                         const u32x2 lo = *(const LAS u32x2*)(CS + l * 256 + (((4 * q + (fq >> 1)) ^ fr) << 4) + (fq & 1) * 8), hi = *(const LAS u32x2*)(CS + l * 256 + (((4 * q + 2 + (fq >> 1)) ^ fr) << 4) + (fq & 1) * 8);
.LBB0_494:
	v_add_u32_e32 v122, 2, v165
	v_xor_b32_e32 v123, v165, v176
	v_xor_b32_e32 v122, v122, v176
	v_add3_u32 v167, 0, v132, v195
	v_lshlrev_b32_e32 v185, 4, v123
	v_lshlrev_b32_e32 v183, 4, v122
	v_add_u32_e32 v123, v167, v185
	v_add_u32_e32 v122, v167, v183
	v_cvt_pk_bf16_f32 v116, v0, v1
	v_cvt_pk_bf16_f32 v117, v2, v3
	v_cvt_pk_bf16_f32 v118, v12, v13
	v_cvt_pk_bf16_f32 v119, v14, v15
	v_cvt_pk_bf16_f32 v124, v4, v5
	v_cvt_pk_bf16_f32 v125, v6, v7
	v_cvt_pk_bf16_f32 v126, v16, v17
	v_cvt_pk_bf16_f32 v127, v18, v19
	ds_read_b64 v[160:161], v123
	ds_read_b64 v[162:163], v122
	v_add_u32_e32 v122, 4, v165
	v_add_u32_e32 v129, 6, v165
	v_xor_b32_e32 v122, v122, v176
	v_xor_b32_e32 v129, v129, v176
	v_lshlrev_b32_e32 v187, 4, v122
	v_lshlrev_b32_e32 v213, 4, v129
	v_add_u32_e32 v122, v167, v187
	v_add_u32_e32 v129, v167, v213
	v_cvt_pk_bf16_f32 v112, v20, v21
	v_cvt_pk_bf16_f32 v113, v22, v23
	v_cvt_pk_bf16_f32 v114, v28, v29
	v_cvt_pk_bf16_f32 v115, v30, v31
	v_cvt_pk_bf16_f32 v120, v24, v25
	v_cvt_pk_bf16_f32 v121, v26, v27
	ds_read_b64 v[132:133], v122
	ds_read_b32 v217, v214 offset:64
	v_cvt_pk_bf16_f32 v122, v32, v33
	v_cvt_pk_bf16_f32 v123, v34, v35
	ds_read_b64 v[134:135], v129
	v_add_u32_e32 v129, 8, v165
	v_add_u32_e32 v130, 10, v165
	v_add_u32_e32 v131, 12, v165
	s_waitcnt lgkmcnt(0)
	v_mfma_f32_16x16x32_bf16 v[168:171], v[116:119], v[160:163], 0
	v_xor_b32_e32 v129, v129, v176
	v_xor_b32_e32 v130, v130, v176
	v_xor_b32_e32 v131, v131, v176
	v_mfma_f32_16x16x32_bf16 v[160:163], v[124:127], v[160:163], 0
	v_lshlrev_b32_e32 v212, 4, v129
	v_lshlrev_b32_e32 v211, 4, v130
	v_lshlrev_b32_e32 v191, 4, v131
	v_add_u32_e32 v129, v167, v212
	v_add_u32_e32 v130, v167, v211
	v_add_u32_e32 v131, v167, v191
	v_cvt_pk_bf16_f32 v108, v36, v37
	v_cvt_pk_bf16_f32 v109, v38, v39
	v_cvt_pk_bf16_f32 v110, v52, v53
	v_cvt_pk_bf16_f32 v111, v54, v55
	v_cvt_pk_bf16_f32 v128, v40, v41
	ds_read_b64 v[172:173], v129
	ds_read_b64 v[174:175], v130
	ds_read_b64 v[218:219], v131
	v_cvt_pk_bf16_f32 v129, v42, v43
	v_cvt_pk_bf16_f32 v130, v56, v57
	v_cvt_pk_bf16_f32 v131, v58, v59
	v_mfma_f32_16x16x32_bf16 v[168:171], v[112:115], v[132:135], v[168:171]
	v_lshlrev_b32_e32 v215, 4, v208
	v_cvt_pk_bf16_f32 v104, v60, v61
	v_cvt_pk_bf16_f32 v105, v62, v63
	v_mfma_f32_16x16x32_bf16 v[160:163], v[120:123], v[132:135], v[160:163]
	v_add_u32_e32 v135, 14, v165
	v_xor_b32_e32 v135, v135, v176
	v_lshlrev_b32_e32 v210, 4, v135
	s_waitcnt lgkmcnt(0)
	v_mfma_f32_16x16x32_bf16 v[168:171], v[108:111], v[172:175], v[168:171]
	v_add_u32_e32 v135, v167, v210
	v_cvt_pk_bf16_f32 v106, v68, v69
	v_cvt_pk_bf16_f32 v107, v70, v71
	v_mfma_f32_16x16x32_bf16 v[160:163], v[128:131], v[172:175], v[160:163]
	v_lshlrev_b32_e32 v172, 2, v164
	v_add_u32_e32 v164, v166, v215
	v_cvt_pk_bf16_f32 v132, v64, v65
	v_cvt_pk_bf16_f32 v133, v66, v67
	v_cvt_pk_bf16_f32 v134, v72, v73
	ds_read_b64 v[220:221], v135
	v_cvt_pk_bf16_f32 v135, v74, v75
	ds_read_b128 v[164:167], v164
	v_ashrrev_i32_e32 v173, 31, v172
	s_waitcnt lgkmcnt(0)
	v_mfma_f32_16x16x32_bf16 v[226:229], v[104:107], v[218:221], v[168:171]
	v_lshl_add_u64 v[198:199], v[172:173], 1, s[0:1]
	v_lshlrev_b32_e32 v222, 16, v166
	v_and_b32_e32 v223, 0xffff0000, v166
	v_mfma_f32_16x16x32_bf16 v[230:233], v[132:135], v[218:221], v[160:163]
	v_lshlrev_b32_e32 v218, 16, v164
	v_and_b32_e32 v219, 0xffff0000, v164
	v_lshlrev_b32_e32 v220, 16, v165
	v_and_b32_e32 v221, 0xffff0000, v165
	v_lshlrev_b32_e32 v224, 16, v167
	v_and_b32_e32 v225, 0xffff0000, v167
	ds_read_b128 v[172:175], v197
	ds_read_b128 v[164:167], v197 offset:16
	ds_read_b128 v[168:171], v197 offset:512
	ds_read_b128 v[160:163], v197 offset:528
	v_cmp_le_i32_e32 vcc, v180, v176
	s_waitcnt lgkmcnt(0)
; #define LAS __attribute__((address_space(3)))
; __device__ __forceinline__ unsigned cvt_pk_bf16(float lo, float hi) { const f32x2 v = {lo, hi}; return __builtin_bit_cast(unsigned, __builtin_convertvector(v, bf16x2_t)); }
; __device__ __forceinline__ u32x4 pack8(const float (&f)[8]) { u32x4 w; w.x = cvt_pk_bf16(f[0], f[1]); w.y = cvt_pk_bf16(f[2], f[3]); w.z = cvt_pk_bf16(f[4], f[5]); w.w = cvt_pk_bf16(f[6], f[7]); return w; }
; template <int MODE> __device__ __forceinline__ void ssd_scan_phase(Frame& F, int j, bool ctx_out) {
;     ...
;                     {
;                         float gg[8]; unpack8(*(const LAS u32x4*)(GS + l * 256 + (((4 * kd + fq) ^ fr) << 4)), gg);
;                         const f32x4 ca = *(const LAS f32x4*)(tab + 32 * kd + 8 * fq), cb = *(const LAS f32x4*)(tab + 32 * kd + 8 * fq + 4);
;                         const f32x4 da = *(const LAS f32x4*)(tab + 128 + 32 * kd + 8 * fq), db = *(const LAS f32x4*)(tab + 128 + 32 * kd + 8 * fq + 4);
;                         const float cs[8] = {ca.x, ca.y, ca.z, ca.w, cb.x, cb.y, cb.z, cb.w}, ds[8] = {da.x, da.y, da.z, da.w, db.x, db.y, db.z, db.w};
;                         float m[8];
; #pragma unroll
;                         for (int jj = 0; jj < 8; ++jj) { const int s = 32 * kd + 8 * fq + jj; const bool valid = dir == 0 ? (s <= l) : (s >= l);
;                             const float e = valid ? __builtin_amdgcn_exp2f(cl - cs[jj]) : 0.f; m[jj] = gg[jj] * e * ds[jj]; if (dir == 0 && s == l) m[jj] += dsk; }
;                         const bf16x8 mf = __builtin_bit_cast(bf16x8, pack8(m));
;                         accd[0] = __builtin_amdgcn_mfma_f32_16x16x32_bf16(xa, mf, accd[0], 0, 0, 0);
;                         accd[1] = __builtin_amdgcn_mfma_f32_16x16x32_bf16(xb, mf, accd[1], 0, 0, 0);
;                     }
;                     const float el = __builtin_amdgcn_exp2f(cl);
; #pragma unroll
;                     for (int pt = 0; pt < 2; ++pt) { const f32x4 y = accd[pt] + acco[pt] * el; u32x2 o; o.x = cvt_pk_bf16(y[0], y[1]); o.y = cvt_pk_bf16(y[2], y[3]);
;                         *(u32x2*)(yout + (size_t)(row0 + l) * DI + h * 64 + ph * 32 + 16 * pt + 4 * fq) = o; }
	v_sub_f32_e32 v236, v216, v172
	v_exp_f32_e32 v236, v236
	v_cndmask_b32_e64 v234, 0, 1, vcc
	v_cmp_ge_i32_e32 vcc, v180, v176
	s_add_i32 s5, s5, s40
	v_sub_f32_e32 v237, v216, v173
	v_cndmask_b32_e64 v235, 0, 1, vcc
	v_cndmask_b32_e64 v234, v235, v234, s[38:39]
	v_and_b32_e32 v234, 1, v234
	v_cmp_eq_u32_e64 s[40:41], 1, v234
	v_cmp_eq_u32_e32 vcc, v180, v176
	s_and_b64 s[42:43], s[38:39], vcc
	v_cndmask_b32_e64 v234, 0, v236, s[40:41]
	v_mul_f32_e32 v218, v234, v218
	v_mul_f32_e32 v234, v168, v218
	v_fma_f32 v218, v168, v218, v203
	v_cndmask_b32_e64 v234, v234, v218, s[42:43]
	v_or_b32_e32 v218, 1, v180
	v_exp_f32_e32 v237, v237
	v_sub_f32_e32 v246, v216, v174
	v_exp_f32_e32 v246, v246
	v_sub_f32_e32 v247, v216, v175
	v_cmp_lt_i32_e32 vcc, v180, v176
	v_cmp_eq_u32_e64 s[100:101], v218, v176
	s_xnor_b64 vcc, vcc, s[38:39]
	s_andn2_b64 s[100:101], s[100:101], s[38:39]
	s_or_b64 vcc, vcc, s[100:101]
	v_exp_f32_e32 v247, v247
	v_sub_f32_e32 v248, v216, v164
	v_cndmask_b32_e32 v235, 0, v237, vcc
	v_mul_f32_e32 v219, v235, v219
	v_cmp_eq_u32_e32 vcc, v218, v176
	v_mul_f32_e32 v235, v169, v219
	v_fma_f32 v219, v169, v219, v203
	s_and_b64 vcc, s[38:39], vcc
	v_cndmask_b32_e32 v235, v235, v219, vcc
	v_or_b32_e32 v219, 2, v180
	v_exp_f32_e32 v248, v248
	v_sub_f32_e32 v249, v216, v165
	v_exp_f32_e32 v249, v249
	v_sub_f32_e32 v240, v216, v166
	v_cmp_le_i32_e32 vcc, v219, v176
	v_cmp_eq_u32_e64 s[100:101], v219, v176
	s_xnor_b64 vcc, vcc, s[38:39]
	s_andn2_b64 s[100:101], s[100:101], s[38:39]
	s_or_b64 vcc, vcc, s[100:101]
	v_exp_f32_e32 v240, v240
	v_sub_f32_e32 v178, v216, v167
	v_cndmask_b32_e32 v236, 0, v246, vcc
	v_mul_f32_e32 v220, v236, v220
	v_cmp_eq_u32_e32 vcc, v219, v176
	v_mul_f32_e32 v236, v170, v220
	v_fma_f32 v220, v170, v220, v203
	s_and_b64 vcc, s[38:39], vcc
	v_cndmask_b32_e32 v236, v236, v220, vcc
	v_or_b32_e32 v220, 3, v180
	v_exp_f32_e32 v178, v178
	v_cvt_pk_bf16_f32 v234, v234, v235
	v_exp_f32_e32 v216, v216
	s_mov_b32 s94, s92
	v_cmp_le_i32_e32 vcc, v220, v176
	v_cmp_eq_u32_e64 s[100:101], v220, v176
	s_xnor_b64 vcc, vcc, s[38:39]
	s_andn2_b64 s[100:101], s[100:101], s[38:39]
	s_or_b64 vcc, vcc, s[100:101]
	s_mov_b32 s95, s92
	s_mov_b32 s93, s92
	v_cndmask_b32_e32 v237, 0, v247, vcc
	v_mul_f32_e32 v221, v237, v221
	v_cmp_eq_u32_e32 vcc, v220, v176
	v_mul_f32_e32 v237, v171, v221
	v_fma_f32 v221, v171, v221, v203
	s_and_b64 vcc, s[38:39], vcc
	v_cndmask_b32_e32 v237, v237, v221, vcc
	v_or_b32_e32 v221, 4, v180
	v_cvt_pk_bf16_f32 v235, v236, v237
	s_nop 0
	s_nop 1
	v_cmp_le_i32_e32 vcc, v221, v176
	v_cmp_eq_u32_e64 s[100:101], v221, v176
	s_xnor_b64 vcc, vcc, s[38:39]
	s_andn2_b64 s[100:101], s[100:101], s[38:39]
	s_or_b64 vcc, vcc, s[100:101]
	v_cndmask_b32_e32 v246, 0, v248, vcc
	v_mul_f32_e32 v222, v246, v222
	v_cmp_eq_u32_e32 vcc, v221, v176
	v_mul_f32_e32 v246, v160, v222
	v_fma_f32 v222, v160, v222, v203
	s_and_b64 vcc, s[38:39], vcc
	v_cndmask_b32_e32 v246, v246, v222, vcc
	v_or_b32_e32 v222, 5, v180
	s_nop 1
	s_nop 1
	v_cmp_le_i32_e32 vcc, v222, v176
	v_cmp_eq_u32_e64 s[100:101], v222, v176
	s_xnor_b64 vcc, vcc, s[38:39]
	s_andn2_b64 s[100:101], s[100:101], s[38:39]
	s_or_b64 vcc, vcc, s[100:101]
	v_cndmask_b32_e32 v247, 0, v249, vcc
	v_mul_f32_e32 v223, v247, v223
	v_cmp_eq_u32_e32 vcc, v222, v176
	v_mul_f32_e32 v247, v161, v223
	v_fma_f32 v223, v161, v223, v203
	s_and_b64 vcc, s[38:39], vcc
	v_cndmask_b32_e32 v247, v247, v223, vcc
	v_or_b32_e32 v223, 6, v180
	v_cvt_pk_bf16_f32 v236, v246, v247
	s_nop 0
	s_nop 1
	v_cmp_le_i32_e32 vcc, v223, v176
	v_cmp_eq_u32_e64 s[100:101], v223, v176
	s_xnor_b64 vcc, vcc, s[38:39]
	s_andn2_b64 s[100:101], s[100:101], s[38:39]
	s_or_b64 vcc, vcc, s[100:101]
	v_cndmask_b32_e32 v240, 0, v240, vcc
	v_mul_f32_e32 v224, v240, v224
	v_cmp_eq_u32_e32 vcc, v223, v176
	v_mul_f32_e32 v240, v162, v224
	v_fma_f32 v224, v162, v224, v203
	s_and_b64 vcc, s[38:39], vcc
	v_cndmask_b32_e32 v240, v240, v224, vcc
	v_or_b32_e32 v224, 7, v180
	s_nop 1
	s_nop 1
	v_cmp_le_i32_e32 vcc, v224, v176
	v_cmp_eq_u32_e64 s[100:101], v224, v176
	s_xnor_b64 vcc, vcc, s[38:39]
	s_andn2_b64 s[100:101], s[100:101], s[38:39]
	s_or_b64 vcc, vcc, s[100:101]
	v_cndmask_b32_e32 v178, 0, v178, vcc
	v_mul_f32_e32 v178, v178, v225
	v_cmp_eq_u32_e32 vcc, v224, v176
	v_mul_f32_e32 v179, v163, v178
	v_fma_f32 v178, v163, v178, v203
	s_and_b64 vcc, s[38:39], vcc
	v_cndmask_b32_e32 v178, v179, v178, vcc
	v_cvt_pk_bf16_f32 v237, v240, v178
	s_and_b64 vcc, exec, s[44:45]
	s_nop 0
	v_mfma_f32_16x16x32_bf16 v[246:249], v[140:143], v[234:237], v[156:159]
	v_mfma_f32_16x16x32_bf16 v[152:155], v[144:147], v[234:237], v[152:155]
	v_add_u32_e32 v234, s5, v176
	v_ashrrev_i32_e32 v235, 31, v234
	v_lshlrev_b64 v[234:235], 13, v[234:235]
	s_nop 3
	v_pk_fma_f32 v[228:229], v[216:217], v[228:229], v[248:249] op_sel_hi:[0,1,1]
	v_pk_fma_f32 v[226:227], v[216:217], v[226:227], v[246:247] op_sel_hi:[0,1,1]
	v_pk_fma_f32 v[154:155], v[216:217], v[232:233], v[154:155] op_sel_hi:[0,1,1]
	v_pk_fma_f32 v[152:153], v[216:217], v[230:231], v[152:153] op_sel_hi:[0,1,1]
	v_lshl_add_u64 v[234:235], v[198:199], 0, v[234:235]
	v_cvt_pk_bf16_f32 v226, v226, v227
	v_cvt_pk_bf16_f32 v227, v228, v229
	v_cvt_pk_bf16_f32 v152, v152, v153
	v_cvt_pk_bf16_f32 v153, v154, v155
	v_or_b32_e32 v216, 16, v176
	v_mov_b64_e32 v[158:159], s[94:95]
	global_store_dwordx2 v[234:235], v[226:227], off
	global_store_dwordx2 v[234:235], v[152:153], off offset:32
	v_lshlrev_b32_e32 v226, 8, v216
	v_mov_b64_e32 v[154:155], s[94:95]
	v_mov_b64_e32 v[156:157], s[92:93]
	v_add_u32_e32 v225, s87, v226
	v_mov_b64_e32 v[152:153], s[92:93]
	s_cbranch_vccz .LBB0_526
	s_and_b64 vcc, exec, s[44:45]
	s_cbranch_vccz .LBB0_527

; #define LAS __attribute__((address_space(3)))
; template <int MODE> __device__ __forceinline__ void ssd_scan_phase(Frame& F, int j, bool ctx_out) {
;     ...
; #pragma unroll
;                     for (int q = 0; q < 4; ++q) {
;                         const u32x2 lo = *(const LAS u32x2*)(CS + l * 256 + (((4 * q + (fq >> 1)) ^ fr) << 4) + (fq & 1) * 8), hi = *(const LAS u32x2*)(CS + l * 256 + (((4 * q + 2 + (fq >> 1)) ^ fr) << 4) + (fq & 1) * 8);
;                         u32x4 c4; c4.x = lo.x; c4.y = lo.y; c4.z = hi.x; c4.w = hi.y; const bf16x8 cfr = __builtin_bit_cast(bf16x8, c4);
;                         acco[0] = __builtin_amdgcn_mfma_f32_16x16x32_bf16(hf[0][q], cfr, acco[0], 0, 0, 0);
;                         acco[1] = __builtin_amdgcn_mfma_f32_16x16x32_bf16(hf[1][q], cfr, acco[1], 0, 0, 0);
;                     }
;                     {
;                         float gg[8]; unpack8(*(const LAS u32x4*)(GS + l * 256 + (((4 * kd + fq) ^ fr) << 4)), gg);
;                         const f32x4 ca = *(const LAS f32x4*)(tab + 32 * kd + 8 * fq), cb = *(const LAS f32x4*)(tab + 32 * kd + 8 * fq + 4);
;                         const f32x4 da = *(const LAS f32x4*)(tab + 128 + 32 * kd + 8 * fq), db = *(const LAS f32x4*)(tab + 128 + 32 * kd + 8 * fq + 4);
;                         const float cs[8] = {ca.x, ca.y, ca.z, ca.w, cb.x, cb.y, cb.z, cb.w}, ds[8] = {da.x, da.y, da.z, da.w, db.x, db.y, db.z, db.w};
;                         float m[8];
; #pragma unroll
;                         for (int jj = 0; jj < 8; ++jj) { const int s = 32 * kd + 8 * fq + jj; const bool valid = dir == 0 ? (s <= l) : (s >= l);
;                             const float e = valid ? __builtin_amdgcn_exp2f(cl - cs[jj]) : 0.f; m[jj] = gg[jj] * e * ds[jj]; if (dir == 0 && s == l) m[jj] += dsk; }
;                         const bf16x8 mf = __builtin_bit_cast(bf16x8, pack8(m));
;                         accd[0] = __builtin_amdgcn_mfma_f32_16x16x32_bf16(xa, mf, accd[0], 0, 0, 0);
;                         accd[1] = __builtin_amdgcn_mfma_f32_16x16x32_bf16(xb, mf, accd[1], 0, 0, 0);
;                     }
;                     const float el = __builtin_amdgcn_exp2f(cl);
; #pragma unroll
;                     for (int pt = 0; pt < 2; ++pt) { const f32x4 y = accd[pt] + acco[pt] * el; u32x2 o; o.x = cvt_pk_bf16(y[0], y[1]); o.y = cvt_pk_bf16(y[2], y[3]);
.LBB0_498:
	v_add3_u32 v178, 0, v226, v195
	v_add_u32_e32 v179, v178, v185
	ds_read_b64 v[226:227], v179
	v_add_u32_e32 v179, v178, v183
	ds_read_b64 v[228:229], v179
	v_add_u32_e32 v179, v178, v187
	ds_read_b64 v[234:235], v179
	v_add_u32_e32 v179, v178, v213
	ds_read_b64 v[236:237], v179
	s_waitcnt lgkmcnt(0)
	v_mfma_f32_16x16x32_bf16 v[230:233], v[116:119], v[226:229], 0
	v_add_u32_e32 v179, v178, v212
	ds_read_b64 v[246:247], v179
	v_add_u32_e32 v179, v178, v211
	v_mfma_f32_16x16x32_bf16 v[226:229], v[124:127], v[226:229], 0
	ds_read_b64 v[248:249], v179
	v_add_u32_e32 v179, v178, v191
	v_add_u32_e32 v178, v178, v210
	v_mfma_f32_16x16x32_bf16 v[230:233], v[112:115], v[234:237], v[230:233]
	v_sub_f32_e32 v172, v217, v172
	v_mfma_f32_16x16x32_bf16 v[226:229], v[120:123], v[234:237], v[226:229]
	ds_read_b64 v[234:235], v179
	v_add_u32_e32 v179, v225, v215
	v_exp_f32_e32 v172, v172
	s_waitcnt lgkmcnt(0)
	v_mfma_f32_16x16x32_bf16 v[230:233], v[108:111], v[246:249], v[230:233]
	v_sub_f32_e32 v173, v217, v173
	v_exp_f32_e32 v173, v173
	v_sub_f32_e32 v174, v217, v174
	v_mfma_f32_16x16x32_bf16 v[226:229], v[128:131], v[246:249], v[226:229]
	ds_read_b128 v[246:249], v179
	ds_read_b64 v[236:237], v178
	v_exp_f32_e32 v174, v174
	v_sub_f32_e32 v164, v217, v164
	v_exp_f32_e32 v164, v164
	s_waitcnt lgkmcnt(0)
	v_lshlrev_b32_e32 v178, 16, v246
	v_and_b32_e32 v179, 0xffff0000, v246
	v_lshlrev_b32_e32 v225, 16, v247
	v_and_b32_e32 v240, 0xffff0000, v247
	v_cmp_le_i32_e32 vcc, v180, v216
	v_cmp_eq_u32_e64 s[100:101], v180, v216
	s_xnor_b64 vcc, vcc, s[38:39]
	s_andn2_b64 s[100:101], s[100:101], s[38:39]
	s_or_b64 vcc, vcc, s[100:101]
	v_mfma_f32_16x16x32_bf16 v[230:233], v[104:107], v[234:237], v[230:233]
	v_cndmask_b32_e32 v172, 0, v172, vcc
	v_mul_f32_e32 v172, v172, v178
	v_cmp_eq_u32_e32 vcc, v180, v216
	v_mul_f32_e32 v178, v168, v172
	s_and_b64 vcc, s[38:39], vcc
	v_fma_f32 v168, v168, v172, v203
	v_cndmask_b32_e32 v168, v178, v168, vcc
	v_cmp_lt_i32_e32 vcc, v180, v216
	v_cmp_eq_u32_e64 s[100:101], v218, v216
	s_xnor_b64 vcc, vcc, s[38:39]
	s_andn2_b64 s[100:101], s[100:101], s[38:39]
	s_or_b64 vcc, vcc, s[100:101]
	v_mfma_f32_16x16x32_bf16 v[226:229], v[132:135], v[234:237], v[226:229]
	v_lshlrev_b32_e32 v234, 16, v248
	v_cndmask_b32_e32 v172, 0, v173, vcc
	v_mul_f32_e32 v172, v172, v179
	v_cmp_eq_u32_e32 vcc, v218, v216
	v_mul_f32_e32 v173, v169, v172
	s_and_b64 vcc, s[38:39], vcc
	v_fma_f32 v169, v169, v172, v203
	v_cndmask_b32_e32 v169, v173, v169, vcc
	v_cmp_le_i32_e32 vcc, v219, v216
	v_cmp_eq_u32_e64 s[100:101], v219, v216
	s_xnor_b64 vcc, vcc, s[38:39]
	s_andn2_b64 s[100:101], s[100:101], s[38:39]
	s_or_b64 vcc, vcc, s[100:101]
	v_sub_f32_e32 v165, v217, v165
	v_exp_f32_e32 v165, v165
	v_cndmask_b32_e32 v172, 0, v174, vcc
	v_mul_f32_e32 v172, v172, v225
	v_cmp_eq_u32_e32 vcc, v219, v216
	v_mul_f32_e32 v173, v170, v172
	s_and_b64 vcc, s[38:39], vcc
	v_fma_f32 v170, v170, v172, v203
	v_cndmask_b32_e32 v170, v173, v170, vcc
	v_sub_f32_e32 v174, v217, v175
	v_exp_f32_e32 v174, v174
	v_cmp_le_i32_e32 vcc, v220, v216
	v_cmp_eq_u32_e64 s[100:101], v220, v216
	s_xnor_b64 vcc, vcc, s[38:39]
	s_andn2_b64 s[100:101], s[100:101], s[38:39]
	s_or_b64 vcc, vcc, s[100:101]
	v_and_b32_e32 v235, 0xffff0000, v248
	v_cndmask_b32_e32 v172, 0, v174, vcc
	v_mul_f32_e32 v172, v172, v240
	v_cmp_eq_u32_e32 vcc, v220, v216
	v_mul_f32_e32 v173, v171, v172
	s_and_b64 vcc, s[38:39], vcc
	v_fma_f32 v171, v171, v172, v203
	v_cndmask_b32_e32 v171, v173, v171, vcc
	v_cmp_le_i32_e32 vcc, v221, v216
	v_cmp_eq_u32_e64 s[100:101], v221, v216
	s_xnor_b64 vcc, vcc, s[38:39]
	s_andn2_b64 s[100:101], s[100:101], s[38:39]
	s_or_b64 vcc, vcc, s[100:101]
	v_sub_f32_e32 v166, v217, v166
	v_exp_f32_e32 v166, v166
	v_cndmask_b32_e32 v164, 0, v164, vcc
	v_mul_f32_e32 v164, v164, v234
	v_cmp_eq_u32_e32 vcc, v221, v216
	v_mul_f32_e32 v172, v160, v164
	s_and_b64 vcc, s[38:39], vcc
	v_fma_f32 v160, v160, v164, v203
	v_cndmask_b32_e32 v164, v172, v160, vcc
	v_cmp_le_i32_e32 vcc, v222, v216
	v_cmp_eq_u32_e64 s[100:101], v222, v216
	s_xnor_b64 vcc, vcc, s[38:39]
	s_andn2_b64 s[100:101], s[100:101], s[38:39]
	s_or_b64 vcc, vcc, s[100:101]
	v_lshlrev_b32_e32 v236, 16, v249
	v_and_b32_e32 v237, 0xffff0000, v249
	v_cndmask_b32_e32 v160, 0, v165, vcc
	v_mul_f32_e32 v160, v160, v235
	v_cmp_eq_u32_e32 vcc, v222, v216
	v_mul_f32_e32 v165, v161, v160
	s_and_b64 vcc, s[38:39], vcc
	v_fma_f32 v160, v161, v160, v203
	v_cndmask_b32_e32 v165, v165, v160, vcc
	v_cmp_le_i32_e32 vcc, v223, v216
	v_cmp_eq_u32_e64 s[100:101], v223, v216
	s_xnor_b64 vcc, vcc, s[38:39]
	s_andn2_b64 s[100:101], s[100:101], s[38:39]
	s_or_b64 vcc, vcc, s[100:101]
	ds_read_b32 v174, v214 offset:128
	s_mov_b32 s94, s92
	v_cndmask_b32_e32 v160, 0, v166, vcc
	v_mul_f32_e32 v160, v160, v236
	v_cmp_eq_u32_e32 vcc, v223, v216
	v_mul_f32_e32 v161, v162, v160
	s_and_b64 vcc, s[38:39], vcc
	v_fma_f32 v160, v162, v160, v203
	v_cndmask_b32_e32 v166, v161, v160, vcc
	v_sub_f32_e32 v162, v217, v167
	v_exp_f32_e32 v162, v162
	v_cmp_le_i32_e32 vcc, v224, v216
	v_cmp_eq_u32_e64 s[100:101], v224, v216
	s_xnor_b64 vcc, vcc, s[38:39]
	s_andn2_b64 s[100:101], s[100:101], s[38:39]
	s_or_b64 vcc, vcc, s[100:101]
	s_mov_b32 s95, s92
	v_or_b32_e32 v173, 32, v176
	v_cndmask_b32_e32 v160, 0, v162, vcc
	v_mul_f32_e32 v160, v160, v237
	v_cmp_eq_u32_e32 vcc, v224, v216
	v_mul_f32_e32 v161, v163, v160
	s_and_b64 vcc, s[38:39], vcc
	v_fma_f32 v160, v163, v160, v203
	v_cndmask_b32_e32 v163, v161, v160, vcc
	v_cvt_pk_bf16_f32 v160, v168, v169
	v_cvt_pk_bf16_f32 v161, v170, v171
	v_cvt_pk_bf16_f32 v162, v164, v165
	v_cvt_pk_bf16_f32 v163, v166, v163
	s_mov_b32 s93, s92
	s_andn2_b64 vcc, exec, s[38:39]
	v_mfma_f32_16x16x32_bf16 v[140:143], v[140:143], v[160:163], v[152:155]
	s_nop 2
	v_exp_f32_e32 v152, v217
	v_mfma_f32_16x16x32_bf16 v[144:147], v[144:147], v[160:163], v[156:159]
	v_add_u32_e32 v154, s5, v216
	v_ashrrev_i32_e32 v155, 31, v154
	v_lshlrev_b64 v[154:155], 13, v[154:155]
	v_pk_fma_f32 v[142:143], v[152:153], v[232:233], v[142:143] op_sel_hi:[0,1,1]
	v_pk_fma_f32 v[140:141], v[152:153], v[230:231], v[140:141] op_sel_hi:[0,1,1]
	v_lshl_add_u64 v[154:155], v[198:199], 0, v[154:155]
	v_cvt_pk_bf16_f32 v140, v140, v141
	v_cvt_pk_bf16_f32 v141, v142, v143
	global_store_dwordx2 v[154:155], v[140:141], off
	v_pk_fma_f32 v[140:141], v[152:153], v[228:229], v[146:147] op_sel_hi:[0,1,1]
	v_pk_fma_f32 v[142:143], v[152:153], v[226:227], v[144:145] op_sel_hi:[0,1,1]
	v_cvt_pk_bf16_f32 v142, v142, v143
	v_cvt_pk_bf16_f32 v143, v140, v141
	global_store_dwordx2 v[154:155], v[142:143], off offset:32
	global_load_dwordx4 v[140:143], v[200:201], off offset:128
	v_cndmask_b32_e64 v152, 0, 1, s[38:39]
	v_mov_b64_e32 v[146:147], s[94:95]
	v_lshlrev_b32_e32 v156, 8, v173
	v_cmp_ne_u32_e64 s[46:47], 1, v152
	v_mov_b64_e32 v[154:155], s[94:95]
	v_mov_b64_e32 v[144:145], s[92:93]
	v_add_u32_e32 v160, s87, v156
	v_mov_b64_e32 v[152:153], s[92:93]
	s_cbranch_vccz .LBB0_528
	s_and_b64 vcc, exec, s[44:45]
	s_cbranch_vccz .LBB0_529

; #define LAS __attribute__((address_space(3)))
; template <int MODE> __device__ __forceinline__ void ssd_scan_phase(Frame& F, int j, bool ctx_out) {
;     ...
; #pragma unroll
;                     for (int q = 0; q < 4; ++q) {
;                         const u32x2 lo = *(const LAS u32x2*)(CS + l * 256 + (((4 * q + (fq >> 1)) ^ fr) << 4) + (fq & 1) * 8), hi = *(const LAS u32x2*)(CS + l * 256 + (((4 * q + 2 + (fq >> 1)) ^ fr) << 4) + (fq & 1) * 8);
;                         u32x4 c4; c4.x = lo.x; c4.y = lo.y; c4.z = hi.x; c4.w = hi.y; const bf16x8 cfr = __builtin_bit_cast(bf16x8, c4);
;                         acco[0] = __builtin_amdgcn_mfma_f32_16x16x32_bf16(hf[0][q], cfr, acco[0], 0, 0, 0);
;                         acco[1] = __builtin_amdgcn_mfma_f32_16x16x32_bf16(hf[1][q], cfr, acco[1], 0, 0, 0);
;                     }
;                     {
;                         float gg[8]; unpack8(*(const LAS u32x4*)(GS + l * 256 + (((4 * kd + fq) ^ fr) << 4)), gg);
;                         const f32x4 ca = *(const LAS f32x4*)(tab + 32 * kd + 8 * fq), cb = *(const LAS f32x4*)(tab + 32 * kd + 8 * fq + 4);
;                         const f32x4 da = *(const LAS f32x4*)(tab + 128 + 32 * kd + 8 * fq), db = *(const LAS f32x4*)(tab + 128 + 32 * kd + 8 * fq + 4);
;                         const float cs[8] = {ca.x, ca.y, ca.z, ca.w, cb.x, cb.y, cb.z, cb.w}, ds[8] = {da.x, da.y, da.z, da.w, db.x, db.y, db.z, db.w};
;                         float m[8];
; #pragma unroll
;                         for (int jj = 0; jj < 8; ++jj) { const int s = 32 * kd + 8 * fq + jj; const bool valid = dir == 0 ? (s <= l) : (s >= l);
;                             const float e = valid ? __builtin_amdgcn_exp2f(cl - cs[jj]) : 0.f; m[jj] = gg[jj] * e * ds[jj]; if (dir == 0 && s == l) m[jj] += dsk; }
.LBB0_502:
	v_add3_u32 v161, 0, v156, v195
	v_add_u32_e32 v156, v161, v185
	v_add_u32_e32 v157, v161, v183
	ds_read_b64 v[162:163], v156
	ds_read_b64 v[164:165], v157
	v_add_u32_e32 v156, v161, v187
	v_add_u32_e32 v158, v161, v213
	ds_read_b64 v[156:157], v156
	ds_read_b32 v175, v214 offset:192
	ds_read_b64 v[158:159], v158
	s_waitcnt lgkmcnt(0)
	v_mfma_f32_16x16x32_bf16 v[166:169], v[116:119], v[162:165], 0
	v_add_u32_e32 v170, v161, v212
	v_add_u32_e32 v171, v161, v211
	v_add_u32_e32 v172, v161, v191
	v_mfma_f32_16x16x32_bf16 v[162:165], v[124:127], v[162:165], 0
	ds_read_b64 v[216:217], v170
	ds_read_b64 v[218:219], v171
	ds_read_b64 v[220:221], v172
	v_add_u32_e32 v161, v161, v210
	v_lshlrev_b32_e32 v172, 4, v207
	v_mfma_f32_16x16x32_bf16 v[166:169], v[112:115], v[156:159], v[166:169]
	ds_read_b64 v[222:223], v161
	v_add_u32_e32 v160, v160, v172
	s_mov_b32 s94, s92
	v_mfma_f32_16x16x32_bf16 v[156:159], v[120:123], v[156:159], v[162:165]
	s_mov_b32 s95, s92
	s_mov_b32 s93, s92
	s_waitcnt lgkmcnt(0)
	v_mfma_f32_16x16x32_bf16 v[162:165], v[108:111], v[216:219], v[166:169]
	s_nop 2
	ds_read_b128 v[168:171], v197 offset:128
	v_mfma_f32_16x16x32_bf16 v[156:159], v[128:131], v[216:219], v[156:159]
	ds_read_b128 v[216:219], v160
	s_waitcnt lgkmcnt(0)
	v_sub_f32_e32 v234, v174, v170
	v_mfma_f32_16x16x32_bf16 v[228:231], v[132:135], v[220:223], v[156:159]
	v_lshlrev_b32_e32 v178, 16, v216
	v_and_b32_e32 v179, 0xffff0000, v216
	v_lshlrev_b32_e32 v232, 16, v219
	s_nop 0
	v_sub_f32_e32 v156, v174, v168
	v_exp_f32_e32 v216, v156
	v_mfma_f32_16x16x32_bf16 v[224:227], v[104:107], v[220:223], v[162:165]
	v_lshlrev_b32_e32 v220, 16, v217
	v_and_b32_e32 v221, 0xffff0000, v217
	v_cndmask_b32_e64 v216, 0, v216, s[40:41]
	ds_read_b128 v[160:163], v197 offset:144
	ds_read_b128 v[164:167], v197 offset:640
	v_mul_f32_e32 v178, v216, v178
	v_and_b32_e32 v233, 0xffff0000, v219
	v_sub_f32_e32 v219, v174, v169
	v_lshlrev_b32_e32 v222, 16, v218
	s_waitcnt lgkmcnt(0)
	v_mul_f32_e32 v216, v164, v178
	v_fma_f32 v178, v164, v178, v203
	v_cndmask_b32_e64 v178, v216, v178, s[42:43]
	v_add_u32_e32 v216, 33, v180
	v_and_b32_e32 v223, 0xffff0000, v218
	v_exp_f32_e32 v219, v219
	v_exp_f32_e32 v234, v234
	v_sub_f32_e32 v235, v174, v171
	v_cmp_le_i32_e32 vcc, v216, v173
	v_cmp_eq_u32_e64 s[100:101], v216, v173
	s_xnor_b64 vcc, vcc, s[38:39]
	s_andn2_b64 s[100:101], s[100:101], s[38:39]
	s_or_b64 vcc, vcc, s[100:101]
	v_exp_f32_e32 v235, v235
	v_sub_f32_e32 v236, v174, v160
	v_cndmask_b32_e32 v217, 0, v219, vcc
	v_mul_f32_e32 v179, v217, v179
	v_cmp_eq_u32_e32 vcc, v216, v173
	v_mul_f32_e32 v217, v165, v179
	v_fma_f32 v179, v165, v179, v203
	s_and_b64 vcc, s[38:39], vcc
	v_cndmask_b32_e32 v179, v217, v179, vcc
	v_add_u32_e32 v217, 34, v180
	v_exp_f32_e32 v236, v236
	ds_read_b128 v[156:159], v197 offset:656
	v_sub_f32_e32 v237, v174, v161
	v_exp_f32_e32 v237, v237
	v_cmp_le_i32_e32 vcc, v217, v173
	v_cmp_eq_u32_e64 s[100:101], v217, v173
	s_xnor_b64 vcc, vcc, s[38:39]
	s_andn2_b64 s[100:101], s[100:101], s[38:39]
	s_or_b64 vcc, vcc, s[100:101]
	v_sub_f32_e32 v240, v174, v162
	v_exp_f32_e32 v240, v240
	v_cndmask_b32_e32 v218, 0, v234, vcc
	v_mul_f32_e32 v218, v218, v220
	v_cmp_eq_u32_e32 vcc, v217, v173
	v_mul_f32_e32 v219, v166, v218
	v_fma_f32 v218, v166, v218, v203
	s_and_b64 vcc, s[38:39], vcc
	v_cndmask_b32_e32 v234, v219, v218, vcc
	v_add_u32_e32 v218, 35, v180
	v_sub_f32_e32 v246, v174, v163
	v_exp_f32_e32 v246, v246
	v_exp_f32_e32 v174, v174
	s_nop 0
	v_cmp_le_i32_e32 vcc, v218, v173
	v_cmp_eq_u32_e64 s[100:101], v218, v173
	s_xnor_b64 vcc, vcc, s[38:39]
	s_andn2_b64 s[100:101], s[100:101], s[38:39]
	s_or_b64 vcc, vcc, s[100:101]
	v_cndmask_b32_e32 v219, 0, v235, vcc
	v_mul_f32_e32 v219, v219, v221
	v_cmp_eq_u32_e32 vcc, v218, v173
	v_mul_f32_e32 v220, v167, v219
	v_fma_f32 v219, v167, v219, v203
	s_and_b64 vcc, s[38:39], vcc
	v_cndmask_b32_e32 v235, v220, v219, vcc
	v_add_u32_e32 v219, 36, v180
	s_nop 1
	s_nop 1
	v_cmp_le_i32_e32 vcc, v219, v173
	v_cmp_eq_u32_e64 s[100:101], v219, v173
	s_xnor_b64 vcc, vcc, s[38:39]
	s_andn2_b64 s[100:101], s[100:101], s[38:39]
	s_or_b64 vcc, vcc, s[100:101]
	v_cndmask_b32_e32 v220, 0, v236, vcc
	v_mul_f32_e32 v220, v220, v222
	v_cmp_eq_u32_e32 vcc, v219, v173
	s_waitcnt lgkmcnt(0)
; __device__ __forceinline__ unsigned cvt_pk_bf16(float lo, float hi) { const f32x2 v = {lo, hi}; return __builtin_bit_cast(unsigned, __builtin_convertvector(v, bf16x2_t)); }
; __device__ __forceinline__ u32x4 pack8(const float (&f)[8]) { u32x4 w; w.x = cvt_pk_bf16(f[0], f[1]); w.y = cvt_pk_bf16(f[2], f[3]); w.z = cvt_pk_bf16(f[4], f[5]); w.w = cvt_pk_bf16(f[6], f[7]); return w; }
; template <int MODE> __device__ __forceinline__ void ssd_scan_phase(Frame& F, int j, bool ctx_out) {
;     ...
; #pragma unroll
;                         for (int jj = 0; jj < 8; ++jj) { const int s = 32 * kd + 8 * fq + jj; const bool valid = dir == 0 ? (s <= l) : (s >= l);
;                             const float e = valid ? __builtin_amdgcn_exp2f(cl - cs[jj]) : 0.f; m[jj] = gg[jj] * e * ds[jj]; if (dir == 0 && s == l) m[jj] += dsk; }
;                         const bf16x8 mf = __builtin_bit_cast(bf16x8, pack8(m));
;                         accd[0] = __builtin_amdgcn_mfma_f32_16x16x32_bf16(xa, mf, accd[0], 0, 0, 0);
;                         accd[1] = __builtin_amdgcn_mfma_f32_16x16x32_bf16(xb, mf, accd[1], 0, 0, 0);
;                     }
;                     const float el = __builtin_amdgcn_exp2f(cl);
; #pragma unroll
;                     for (int pt = 0; pt < 2; ++pt) { const f32x4 y = accd[pt] + acco[pt] * el; u32x2 o; o.x = cvt_pk_bf16(y[0], y[1]); o.y = cvt_pk_bf16(y[2], y[3]);
;                         *(u32x2*)(yout + (size_t)(row0 + l) * DI + h * 64 + ph * 32 + 16 * pt + 4 * fq) = o; }
	v_mul_f32_e32 v221, v156, v220
	v_fma_f32 v220, v156, v220, v203
	s_and_b64 vcc, s[38:39], vcc
	v_cndmask_b32_e32 v236, v221, v220, vcc
	v_add_u32_e32 v220, 37, v180
	s_nop 1
	s_nop 1
	v_cmp_le_i32_e32 vcc, v220, v173
	v_cmp_eq_u32_e64 s[100:101], v220, v173
	s_xnor_b64 vcc, vcc, s[38:39]
	s_andn2_b64 s[100:101], s[100:101], s[38:39]
	s_or_b64 vcc, vcc, s[100:101]
	v_cndmask_b32_e32 v221, 0, v237, vcc
	v_mul_f32_e32 v221, v221, v223
	v_cmp_eq_u32_e32 vcc, v220, v173
	v_mul_f32_e32 v222, v157, v221
	v_fma_f32 v221, v157, v221, v203
	s_and_b64 vcc, s[38:39], vcc
	v_cndmask_b32_e32 v223, v222, v221, vcc
	v_add_u32_e32 v221, 38, v180
	s_nop 1
	s_nop 1
	v_cmp_le_i32_e32 vcc, v221, v173
	v_cmp_eq_u32_e64 s[100:101], v221, v173
	s_xnor_b64 vcc, vcc, s[38:39]
	s_andn2_b64 s[100:101], s[100:101], s[38:39]
	s_or_b64 vcc, vcc, s[100:101]
	v_cndmask_b32_e32 v222, 0, v240, vcc
	v_mul_f32_e32 v222, v222, v232
	v_cmp_eq_u32_e32 vcc, v221, v173
	v_mul_f32_e32 v232, v158, v222
	v_fma_f32 v222, v158, v222, v203
	s_and_b64 vcc, s[38:39], vcc
	v_cndmask_b32_e32 v237, v232, v222, vcc
	v_add_u32_e32 v222, 39, v180
	s_nop 1
	s_nop 1
	v_cmp_le_i32_e32 vcc, v222, v173
	v_cmp_eq_u32_e64 s[100:101], v222, v173
	s_xnor_b64 vcc, vcc, s[38:39]
	s_andn2_b64 s[100:101], s[100:101], s[38:39]
	s_or_b64 vcc, vcc, s[100:101]
	v_cndmask_b32_e32 v232, 0, v246, vcc
	v_mul_f32_e32 v232, v232, v233
	v_cmp_eq_u32_e32 vcc, v222, v173
	v_mul_f32_e32 v233, v159, v232
	v_fma_f32 v232, v159, v232, v203
	s_and_b64 vcc, s[38:39], vcc
	v_cndmask_b32_e32 v240, v233, v232, vcc
	v_cvt_pk_bf16_f32 v232, v178, v179
	v_cvt_pk_bf16_f32 v233, v234, v235
	v_cvt_pk_bf16_f32 v234, v236, v223
	v_cvt_pk_bf16_f32 v235, v237, v240
	s_and_b64 vcc, exec, s[46:47]
	s_waitcnt vmcnt(5)
	v_mfma_f32_16x16x32_bf16 v[144:147], v[148:151], v[232:235], v[144:147]
	v_mfma_f32_16x16x32_bf16 v[246:249], v[136:139], v[232:235], v[152:155]
	v_add_u32_e32 v232, s5, v173
	v_ashrrev_i32_e32 v233, 31, v232
	v_lshlrev_b64 v[232:233], 13, v[232:233]
	s_nop 3
	v_pk_fma_f32 v[146:147], v[174:175], v[230:231], v[146:147] op_sel_hi:[0,1,1]
	v_pk_fma_f32 v[144:145], v[174:175], v[228:229], v[144:145] op_sel_hi:[0,1,1]
	v_lshl_add_u64 v[232:233], v[198:199], 0, v[232:233]
	v_cvt_pk_bf16_f32 v144, v144, v145
	v_cvt_pk_bf16_f32 v145, v146, v147
	v_or_b32_e32 v173, 48, v176
	v_mov_b64_e32 v[154:155], s[94:95]
	v_pk_fma_f32 v[226:227], v[174:175], v[226:227], v[248:249] op_sel_hi:[0,1,1]
	v_pk_fma_f32 v[224:225], v[174:175], v[224:225], v[246:247] op_sel_hi:[0,1,1]
	global_store_dwordx2 v[232:233], v[144:145], off offset:32
	v_lshlrev_b32_e32 v223, 8, v173
	v_mov_b64_e32 v[146:147], s[94:95]
	v_mov_b64_e32 v[152:153], s[92:93]
	v_cvt_pk_bf16_f32 v224, v224, v225
	v_cvt_pk_bf16_f32 v225, v226, v227
	v_add_u32_e32 v174, s87, v223
	v_mov_b64_e32 v[144:145], s[92:93]
	global_store_dwordx2 v[232:233], v[224:225], off
	s_cbranch_vccz .LBB0_530
	s_and_b64 vcc, exec, s[44:45]
	s_cbranch_vccz .LBB0_531

; #define LAS __attribute__((address_space(3)))
; template <int MODE> __device__ __forceinline__ void ssd_scan_phase(Frame& F, int j, bool ctx_out) {
;     ...
; #pragma unroll
;                     for (int q = 0; q < 4; ++q) {
;                         const u32x2 lo = *(const LAS u32x2*)(CS + l * 256 + (((4 * q + (fq >> 1)) ^ fr) << 4) + (fq & 1) * 8), hi = *(const LAS u32x2*)(CS + l * 256 + (((4 * q + 2 + (fq >> 1)) ^ fr) << 4) + (fq & 1) * 8);
;                         u32x4 c4; c4.x = lo.x; c4.y = lo.y; c4.z = hi.x; c4.w = hi.y; const bf16x8 cfr = __builtin_bit_cast(bf16x8, c4);
;                         acco[0] = __builtin_amdgcn_mfma_f32_16x16x32_bf16(hf[0][q], cfr, acco[0], 0, 0, 0);
;                         acco[1] = __builtin_amdgcn_mfma_f32_16x16x32_bf16(hf[1][q], cfr, acco[1], 0, 0, 0);
;                     }
;                     {
;                         float gg[8]; unpack8(*(const LAS u32x4*)(GS + l * 256 + (((4 * kd + fq) ^ fr) << 4)), gg);
;                         const f32x4 ca = *(const LAS f32x4*)(tab + 32 * kd + 8 * fq), cb = *(const LAS f32x4*)(tab + 32 * kd + 8 * fq + 4);
;                         const f32x4 da = *(const LAS f32x4*)(tab + 128 + 32 * kd + 8 * fq), db = *(const LAS f32x4*)(tab + 128 + 32 * kd + 8 * fq + 4);
;                         const float cs[8] = {ca.x, ca.y, ca.z, ca.w, cb.x, cb.y, cb.z, cb.w}, ds[8] = {da.x, da.y, da.z, da.w, db.x, db.y, db.z, db.w};
;                         float m[8];
; #pragma unroll
;                         for (int jj = 0; jj < 8; ++jj) { const int s = 32 * kd + 8 * fq + jj; const bool valid = dir == 0 ? (s <= l) : (s >= l);
;                             const float e = valid ? __builtin_amdgcn_exp2f(cl - cs[jj]) : 0.f; m[jj] = gg[jj] * e * ds[jj]; if (dir == 0 && s == l) m[jj] += dsk; }
;                         const bf16x8 mf = __builtin_bit_cast(bf16x8, pack8(m));
;                         accd[0] = __builtin_amdgcn_mfma_f32_16x16x32_bf16(xa, mf, accd[0], 0, 0, 0);
;                         accd[1] = __builtin_amdgcn_mfma_f32_16x16x32_bf16(xb, mf, accd[1], 0, 0, 0);
;                     }
;                     const float el = __builtin_amdgcn_exp2f(cl);
; #pragma unroll
;                     for (int pt = 0; pt < 2; ++pt) { const f32x4 y = accd[pt] + acco[pt] * el; u32x2 o; o.x = cvt_pk_bf16(y[0], y[1]); o.y = cvt_pk_bf16(y[2], y[3]);
.LBB0_506:
	v_add3_u32 v178, 0, v223, v195
	v_add_u32_e32 v179, v178, v185
	ds_read_b64 v[224:225], v179
	v_add_u32_e32 v179, v178, v183
	ds_read_b64 v[226:227], v179
	v_add_u32_e32 v179, v178, v187
	ds_read_b64 v[232:233], v179
	v_add_u32_e32 v179, v178, v213
	ds_read_b64 v[234:235], v179
	s_waitcnt lgkmcnt(2)
	v_mfma_f32_16x16x32_bf16 v[228:231], v[116:119], v[224:227], 0
	v_add_u32_e32 v179, v178, v212
	ds_read_b64 v[246:247], v179
	v_add_u32_e32 v179, v178, v211
	v_mfma_f32_16x16x32_bf16 v[224:227], v[124:127], v[224:227], 0
	ds_read_b64 v[248:249], v179
	v_add_u32_e32 v174, v174, v172
	v_sub_f32_e32 v168, v175, v168
	s_waitcnt lgkmcnt(2)
	v_mfma_f32_16x16x32_bf16 v[228:231], v[112:115], v[232:235], v[228:231]
	v_exp_f32_e32 v168, v168
	v_add_u32_e32 v179, v178, v191
	v_add_u32_e32 v178, v178, v210
	v_mfma_f32_16x16x32_bf16 v[224:227], v[120:123], v[232:235], v[224:227]
	ds_read_b64 v[232:233], v179
	ds_read_b64 v[234:235], v178
	v_sub_f32_e32 v169, v175, v169
	s_waitcnt lgkmcnt(2)
	v_mfma_f32_16x16x32_bf16 v[228:231], v[108:111], v[246:249], v[228:231]
	v_exp_f32_e32 v169, v169
	v_sub_f32_e32 v170, v175, v170
	v_exp_f32_e32 v170, v170
	v_mfma_f32_16x16x32_bf16 v[224:227], v[128:131], v[246:249], v[224:227]
	ds_read_b128 v[246:249], v174
	v_add_u32_e32 v174, 32, v180
	s_waitcnt lgkmcnt(1)
	v_mfma_f32_16x16x32_bf16 v[228:231], v[104:107], v[232:235], v[228:231]
	v_cmp_le_i32_e32 vcc, v174, v173
	v_cmp_eq_u32_e64 s[100:101], v174, v173
	s_xnor_b64 vcc, vcc, s[38:39]
	s_andn2_b64 s[100:101], s[100:101], s[38:39]
	s_or_b64 vcc, vcc, s[100:101]
	s_waitcnt lgkmcnt(0)
	v_lshlrev_b32_e32 v178, 16, v246
	v_cndmask_b32_e32 v168, 0, v168, vcc
	v_mul_f32_e32 v168, v168, v178
	v_cmp_eq_u32_e32 vcc, v174, v173
	v_mul_f32_e32 v178, v164, v168
	s_and_b64 vcc, s[38:39], vcc
	v_fma_f32 v164, v164, v168, v203
	v_cndmask_b32_e32 v164, v178, v164, vcc
	v_and_b32_e32 v179, 0xffff0000, v246
	v_cmp_le_i32_e32 vcc, v216, v173
	v_cmp_eq_u32_e64 s[100:101], v216, v173
	s_xnor_b64 vcc, vcc, s[38:39]
	s_andn2_b64 s[100:101], s[100:101], s[38:39]
	s_or_b64 vcc, vcc, s[100:101]
	v_lshlrev_b32_e32 v223, 16, v247
	v_cndmask_b32_e32 v168, 0, v169, vcc
	v_mul_f32_e32 v168, v168, v179
	v_cmp_eq_u32_e32 vcc, v216, v173
	v_mul_f32_e32 v169, v165, v168
	s_and_b64 vcc, s[38:39], vcc
	v_fma_f32 v165, v165, v168, v203
	v_cndmask_b32_e32 v165, v169, v165, vcc
	v_cmp_le_i32_e32 vcc, v217, v173
	v_cmp_eq_u32_e64 s[100:101], v217, v173
	s_xnor_b64 vcc, vcc, s[38:39]
	s_andn2_b64 s[100:101], s[100:101], s[38:39]
	s_or_b64 vcc, vcc, s[100:101]
	v_mfma_f32_16x16x32_bf16 v[224:227], v[132:135], v[232:235], v[224:227]
	v_and_b32_e32 v232, 0xffff0000, v247
	v_cndmask_b32_e32 v168, 0, v170, vcc
	v_mul_f32_e32 v168, v168, v223
	v_cmp_eq_u32_e32 vcc, v217, v173
	v_mul_f32_e32 v169, v166, v168
	s_and_b64 vcc, s[38:39], vcc
	v_fma_f32 v166, v166, v168, v203
	v_cndmask_b32_e32 v166, v169, v166, vcc
	v_sub_f32_e32 v170, v175, v171
	v_exp_f32_e32 v170, v170
	v_cmp_le_i32_e32 vcc, v218, v173
	v_cmp_eq_u32_e64 s[100:101], v218, v173
	s_xnor_b64 vcc, vcc, s[38:39]
	s_andn2_b64 s[100:101], s[100:101], s[38:39]
	s_or_b64 vcc, vcc, s[100:101]
	v_sub_f32_e32 v160, v175, v160
	v_cndmask_b32_e32 v168, 0, v170, vcc
	v_mul_f32_e32 v168, v168, v232
	v_cmp_eq_u32_e32 vcc, v218, v173
	v_mul_f32_e32 v169, v167, v168
	s_and_b64 vcc, s[38:39], vcc
	v_fma_f32 v167, v167, v168, v203
	v_cndmask_b32_e32 v167, v169, v167, vcc
	v_exp_f32_e32 v160, v160
	v_cmp_le_i32_e32 vcc, v219, v173
	v_cmp_eq_u32_e64 s[100:101], v219, v173
	s_xnor_b64 vcc, vcc, s[38:39]
	s_andn2_b64 s[100:101], s[100:101], s[38:39]
	s_or_b64 vcc, vcc, s[100:101]
	v_lshlrev_b32_e32 v233, 16, v248
	v_cndmask_b32_e32 v160, 0, v160, vcc
	v_mul_f32_e32 v160, v160, v233
	v_cmp_eq_u32_e32 vcc, v219, v173
	v_mul_f32_e32 v168, v156, v160
	s_and_b64 vcc, s[38:39], vcc
	v_fma_f32 v156, v156, v160, v203
	v_cndmask_b32_e32 v160, v168, v156, vcc
	v_sub_f32_e32 v161, v175, v161
	v_exp_f32_e32 v161, v161
	v_cmp_le_i32_e32 vcc, v220, v173
	v_cmp_eq_u32_e64 s[100:101], v220, v173
	s_xnor_b64 vcc, vcc, s[38:39]
	s_andn2_b64 s[100:101], s[100:101], s[38:39]
	s_or_b64 vcc, vcc, s[100:101]
	v_and_b32_e32 v234, 0xffff0000, v248
	v_cndmask_b32_e32 v156, 0, v161, vcc
	v_mul_f32_e32 v156, v156, v234
	v_cmp_eq_u32_e32 vcc, v220, v173
	v_mul_f32_e32 v161, v157, v156
	s_and_b64 vcc, s[38:39], vcc
	v_fma_f32 v156, v157, v156, v203
	v_cndmask_b32_e32 v161, v161, v156, vcc
	v_sub_f32_e32 v162, v175, v162
	v_exp_f32_e32 v162, v162
	v_cmp_le_i32_e32 vcc, v221, v173
	v_cmp_eq_u32_e64 s[100:101], v221, v173
	s_xnor_b64 vcc, vcc, s[38:39]
	s_andn2_b64 s[100:101], s[100:101], s[38:39]
	s_or_b64 vcc, vcc, s[100:101]
	v_lshlrev_b32_e32 v235, 16, v249
	v_cndmask_b32_e32 v156, 0, v162, vcc
	v_mul_f32_e32 v156, v156, v235
	v_cmp_eq_u32_e32 vcc, v221, v173
	v_mul_f32_e32 v157, v158, v156
	s_and_b64 vcc, s[38:39], vcc
	v_fma_f32 v156, v158, v156, v203
	v_cndmask_b32_e32 v162, v157, v156, vcc
	v_sub_f32_e32 v158, v175, v163
	v_exp_f32_e32 v158, v158
	v_cmp_le_i32_e32 vcc, v222, v173
	v_cmp_eq_u32_e64 s[100:101], v222, v173
	s_xnor_b64 vcc, vcc, s[38:39]
	s_andn2_b64 s[100:101], s[100:101], s[38:39]
	s_or_b64 vcc, vcc, s[100:101]
	v_and_b32_e32 v236, 0xffff0000, v249
	ds_read_b32 v170, v214 offset:256
	v_cndmask_b32_e32 v156, 0, v158, vcc
	v_mul_f32_e32 v156, v156, v236
	v_cmp_eq_u32_e32 vcc, v222, v173
	v_mul_f32_e32 v157, v159, v156
	s_and_b64 vcc, s[38:39], vcc
	v_fma_f32 v156, v159, v156, v203
	v_cndmask_b32_e32 v159, v157, v156, vcc
	v_cvt_pk_bf16_f32 v156, v164, v165
	v_cvt_pk_bf16_f32 v157, v166, v167
	v_cvt_pk_bf16_f32 v158, v160, v161
	v_cvt_pk_bf16_f32 v159, v162, v159
	s_mov_b32 s94, s92
	s_mov_b32 s95, s92
	v_mfma_f32_16x16x32_bf16 v[136:139], v[136:139], v[156:159], v[144:147]
	v_or_b32_e32 v169, 64, v176
	s_mov_b32 s93, s92
	s_and_b64 vcc, exec, s[46:47]
	v_mfma_f32_16x16x32_bf16 v[144:147], v[148:151], v[156:159], v[152:155]
	v_exp_f32_e32 v148, v175
	v_add_u32_e32 v150, s5, v173
	v_ashrrev_i32_e32 v151, 31, v150
	v_lshlrev_b64 v[150:151], 13, v[150:151]
	v_pk_fma_f32 v[138:139], v[148:149], v[230:231], v[138:139] op_sel_hi:[0,1,1]
	v_pk_fma_f32 v[136:137], v[148:149], v[228:229], v[136:137] op_sel_hi:[0,1,1]
	v_lshl_add_u64 v[150:151], v[198:199], 0, v[150:151]
	v_cvt_pk_bf16_f32 v136, v136, v137
	v_cvt_pk_bf16_f32 v137, v138, v139
	global_store_dwordx2 v[150:151], v[136:137], off
	v_pk_fma_f32 v[136:137], v[148:149], v[226:227], v[146:147] op_sel_hi:[0,1,1]
	v_pk_fma_f32 v[138:139], v[148:149], v[224:225], v[144:145] op_sel_hi:[0,1,1]
	v_cvt_pk_bf16_f32 v138, v138, v139
	v_cvt_pk_bf16_f32 v139, v136, v137
	global_store_dwordx2 v[150:151], v[138:139], off offset:32
	global_load_dwordx4 v[136:139], v[200:201], off offset:192
	v_mov_b64_e32 v[146:147], s[94:95]
	v_lshlrev_b32_e32 v152, 8, v169
	v_mov_b64_e32 v[150:151], s[94:95]
	v_mov_b64_e32 v[144:145], s[92:93]
	v_add_u32_e32 v156, s87, v152
	v_mov_b64_e32 v[148:149], s[92:93]
	s_cbranch_vccz .LBB0_532
	s_and_b64 vcc, exec, s[46:47]
	s_cbranch_vccz .LBB0_533

; #define LAS __attribute__((address_space(3)))
; template <int MODE> __device__ __forceinline__ void ssd_scan_phase(Frame& F, int j, bool ctx_out) {
;     ...
; #pragma unroll
;                     for (int q = 0; q < 4; ++q) {
;                         const u32x2 lo = *(const LAS u32x2*)(CS + l * 256 + (((4 * q + (fq >> 1)) ^ fr) << 4) + (fq & 1) * 8), hi = *(const LAS u32x2*)(CS + l * 256 + (((4 * q + 2 + (fq >> 1)) ^ fr) << 4) + (fq & 1) * 8);
;                         u32x4 c4; c4.x = lo.x; c4.y = lo.y; c4.z = hi.x; c4.w = hi.y; const bf16x8 cfr = __builtin_bit_cast(bf16x8, c4);
;                         acco[0] = __builtin_amdgcn_mfma_f32_16x16x32_bf16(hf[0][q], cfr, acco[0], 0, 0, 0);
;                         acco[1] = __builtin_amdgcn_mfma_f32_16x16x32_bf16(hf[1][q], cfr, acco[1], 0, 0, 0);
;                     }
;                     {
;                         float gg[8]; unpack8(*(const LAS u32x4*)(GS + l * 256 + (((4 * kd + fq) ^ fr) << 4)), gg);
;                         const f32x4 ca = *(const LAS f32x4*)(tab + 32 * kd + 8 * fq), cb = *(const LAS f32x4*)(tab + 32 * kd + 8 * fq + 4);
;                         const f32x4 da = *(const LAS f32x4*)(tab + 128 + 32 * kd + 8 * fq), db = *(const LAS f32x4*)(tab + 128 + 32 * kd + 8 * fq + 4);
;                         const float cs[8] = {ca.x, ca.y, ca.z, ca.w, cb.x, cb.y, cb.z, cb.w}, ds[8] = {da.x, da.y, da.z, da.w, db.x, db.y, db.z, db.w};
;                         float m[8];
; #pragma unroll
;                         for (int jj = 0; jj < 8; ++jj) { const int s = 32 * kd + 8 * fq + jj; const bool valid = dir == 0 ? (s <= l) : (s >= l);
;                             const float e = valid ? __builtin_amdgcn_exp2f(cl - cs[jj]) : 0.f; m[jj] = gg[jj] * e * ds[jj]; if (dir == 0 && s == l) m[jj] += dsk; }
.LBB0_510:
	v_add3_u32 v157, 0, v152, v195
	v_add_u32_e32 v152, v157, v185
	v_add_u32_e32 v153, v157, v183
	ds_read_b64 v[158:159], v152
	ds_read_b64 v[160:161], v153
	v_add_u32_e32 v152, v157, v187
	v_add_u32_e32 v154, v157, v213
	ds_read_b64 v[152:153], v152
	ds_read_b32 v171, v214 offset:320
	ds_read_b64 v[154:155], v154
	s_waitcnt lgkmcnt(3)
	v_mfma_f32_16x16x32_bf16 v[162:165], v[116:119], v[158:161], 0
	v_add_u32_e32 v166, v157, v212
	v_add_u32_e32 v167, v157, v211
	v_add_u32_e32 v168, v157, v191
	v_mfma_f32_16x16x32_bf16 v[158:161], v[124:127], v[158:161], 0
	ds_read_b64 v[216:217], v166
	ds_read_b64 v[218:219], v167
	ds_read_b64 v[220:221], v168
	v_add_u32_e32 v157, v157, v210
	ds_read_b64 v[222:223], v157
	s_waitcnt lgkmcnt(4)
	v_mfma_f32_16x16x32_bf16 v[162:165], v[112:115], v[152:155], v[162:165]
	v_lshlrev_b32_e32 v168, 4, v206
	v_add_u32_e32 v156, v156, v168
	s_mov_b32 s94, s92
	v_mfma_f32_16x16x32_bf16 v[152:155], v[120:123], v[152:155], v[158:161]
	s_mov_b32 s95, s92
	s_mov_b32 s93, s92
	s_waitcnt lgkmcnt(2)
	v_mfma_f32_16x16x32_bf16 v[158:161], v[108:111], v[216:219], v[162:165]
	s_nop 2
	ds_read_b128 v[164:167], v197 offset:256
	v_mfma_f32_16x16x32_bf16 v[152:155], v[128:131], v[216:219], v[152:155]
	ds_read_b128 v[216:219], v156
	s_waitcnt lgkmcnt(1)
	v_sub_f32_e32 v228, v170, v165
	v_mfma_f32_16x16x32_bf16 v[224:227], v[104:107], v[220:223], v[158:161]
	s_waitcnt lgkmcnt(0)
	v_lshlrev_b32_e32 v173, 16, v216
	v_and_b32_e32 v174, 0xffff0000, v216
	v_lshlrev_b32_e32 v175, 16, v217
	v_mfma_f32_16x16x32_bf16 v[220:223], v[132:135], v[220:223], v[152:155]
	ds_read_b128 v[156:159], v197 offset:272
	ds_read_b128 v[160:163], v197 offset:768
	v_and_b32_e32 v178, 0xffff0000, v217
	v_sub_f32_e32 v152, v170, v164
	v_exp_f32_e32 v200, v152
	v_lshlrev_b32_e32 v179, 16, v218
	v_and_b32_e32 v216, 0xffff0000, v218
	v_lshlrev_b32_e32 v217, 16, v219
	v_cndmask_b32_e64 v200, 0, v200, s[40:41]
	v_mul_f32_e32 v173, v200, v173
	s_waitcnt lgkmcnt(0)
	v_mul_f32_e32 v200, v160, v173
	v_fma_f32 v173, v160, v173, v203
	v_and_b32_e32 v218, 0xffff0000, v219
	v_cndmask_b32_e64 v219, v200, v173, s[42:43]
	v_add_u32_e32 v173, 0x41, v180
	v_exp_f32_e32 v228, v228
	v_sub_f32_e32 v229, v170, v166
	v_exp_f32_e32 v229, v229
	v_sub_f32_e32 v230, v170, v167
	v_cmp_le_i32_e32 vcc, v173, v169
	v_cmp_eq_u32_e64 s[100:101], v173, v169
	s_xnor_b64 vcc, vcc, s[38:39]
	s_andn2_b64 s[100:101], s[100:101], s[38:39]
	s_or_b64 vcc, vcc, s[100:101]
	v_exp_f32_e32 v230, v230
	v_sub_f32_e32 v231, v170, v156
	v_cndmask_b32_e32 v200, 0, v228, vcc
	v_mul_f32_e32 v174, v200, v174
	v_cmp_eq_u32_e32 vcc, v173, v169
	v_mul_f32_e32 v200, v161, v174
	v_fma_f32 v174, v161, v174, v203
	s_and_b64 vcc, s[38:39], vcc
	v_cndmask_b32_e32 v228, v200, v174, vcc
	v_add_u32_e32 v174, 0x42, v180
	v_exp_f32_e32 v231, v231
	ds_read_b128 v[152:155], v197 offset:784
	v_sub_f32_e32 v232, v170, v157
	v_exp_f32_e32 v232, v232
	v_cmp_le_i32_e32 vcc, v174, v169
	v_cmp_eq_u32_e64 s[100:101], v174, v169
	s_xnor_b64 vcc, vcc, s[38:39]
	s_andn2_b64 s[100:101], s[100:101], s[38:39]
	s_or_b64 vcc, vcc, s[100:101]
	v_sub_f32_e32 v233, v170, v158
	v_exp_f32_e32 v233, v233
	v_cndmask_b32_e32 v200, 0, v229, vcc
	v_mul_f32_e32 v175, v200, v175
	v_cmp_eq_u32_e32 vcc, v174, v169
	v_mul_f32_e32 v200, v162, v175
	v_fma_f32 v175, v162, v175, v203
	s_and_b64 vcc, s[38:39], vcc
	v_cndmask_b32_e32 v229, v200, v175, vcc
	v_add_u32_e32 v175, 0x43, v180
	v_sub_f32_e32 v234, v170, v159
	v_exp_f32_e32 v234, v234
	v_cvt_pk_bf16_f32 v228, v219, v228
	v_exp_f32_e32 v170, v170
	v_cmp_le_i32_e32 vcc, v175, v169
	v_cmp_eq_u32_e64 s[100:101], v175, v169
	s_xnor_b64 vcc, vcc, s[38:39]
	s_andn2_b64 s[100:101], s[100:101], s[38:39]
	s_or_b64 vcc, vcc, s[100:101]
	v_cndmask_b32_e32 v200, 0, v230, vcc
	v_mul_f32_e32 v178, v200, v178
	v_cmp_eq_u32_e32 vcc, v175, v169
	v_mul_f32_e32 v200, v163, v178
	v_fma_f32 v178, v163, v178, v203
	s_and_b64 vcc, s[38:39], vcc
	v_cndmask_b32_e32 v178, v200, v178, vcc
	v_add_u32_e32 v200, 0x44, v180
	v_cvt_pk_bf16_f32 v229, v229, v178
	s_nop 0
	s_nop 1
	v_cmp_le_i32_e32 vcc, v200, v169
	v_cmp_eq_u32_e64 s[100:101], v200, v169
	s_xnor_b64 vcc, vcc, s[38:39]
	s_andn2_b64 s[100:101], s[100:101], s[38:39]
	s_or_b64 vcc, vcc, s[100:101]
	v_cndmask_b32_e32 v201, 0, v231, vcc
	v_mul_f32_e32 v179, v201, v179
	v_cmp_eq_u32_e32 vcc, v200, v169
	s_waitcnt lgkmcnt(0)
; __device__ __forceinline__ unsigned cvt_pk_bf16(float lo, float hi) { const f32x2 v = {lo, hi}; return __builtin_bit_cast(unsigned, __builtin_convertvector(v, bf16x2_t)); }
; __device__ __forceinline__ u32x4 pack8(const float (&f)[8]) { u32x4 w; w.x = cvt_pk_bf16(f[0], f[1]); w.y = cvt_pk_bf16(f[2], f[3]); w.z = cvt_pk_bf16(f[4], f[5]); w.w = cvt_pk_bf16(f[6], f[7]); return w; }
; template <int MODE> __device__ __forceinline__ void ssd_scan_phase(Frame& F, int j, bool ctx_out) {
;     ...
; #pragma unroll
;                         for (int jj = 0; jj < 8; ++jj) { const int s = 32 * kd + 8 * fq + jj; const bool valid = dir == 0 ? (s <= l) : (s >= l);
;                             const float e = valid ? __builtin_amdgcn_exp2f(cl - cs[jj]) : 0.f; m[jj] = gg[jj] * e * ds[jj]; if (dir == 0 && s == l) m[jj] += dsk; }
;                         const bf16x8 mf = __builtin_bit_cast(bf16x8, pack8(m));
;                         accd[0] = __builtin_amdgcn_mfma_f32_16x16x32_bf16(xa, mf, accd[0], 0, 0, 0);
;                         accd[1] = __builtin_amdgcn_mfma_f32_16x16x32_bf16(xb, mf, accd[1], 0, 0, 0);
;                     }
;                     const float el = __builtin_amdgcn_exp2f(cl);
; #pragma unroll
;                     for (int pt = 0; pt < 2; ++pt) { const f32x4 y = accd[pt] + acco[pt] * el; u32x2 o; o.x = cvt_pk_bf16(y[0], y[1]); o.y = cvt_pk_bf16(y[2], y[3]);
;                         *(u32x2*)(yout + (size_t)(row0 + l) * DI + h * 64 + ph * 32 + 16 * pt + 4 * fq) = o; }
	v_mul_f32_e32 v201, v152, v179
	v_fma_f32 v179, v152, v179, v203
	s_and_b64 vcc, s[38:39], vcc
	v_cndmask_b32_e32 v179, v201, v179, vcc
	v_add_u32_e32 v201, 0x45, v180
	s_nop 1
	s_nop 1
	v_cmp_le_i32_e32 vcc, v201, v169
	v_cmp_eq_u32_e64 s[100:101], v201, v169
	s_xnor_b64 vcc, vcc, s[38:39]
	s_andn2_b64 s[100:101], s[100:101], s[38:39]
	s_or_b64 vcc, vcc, s[100:101]
	v_cndmask_b32_e32 v230, 0, v232, vcc
	v_mul_f32_e32 v216, v230, v216
	v_cmp_eq_u32_e32 vcc, v201, v169
	v_mul_f32_e32 v230, v153, v216
	v_fma_f32 v216, v153, v216, v203
	s_and_b64 vcc, s[38:39], vcc
	v_cndmask_b32_e32 v230, v230, v216, vcc
	v_add_u32_e32 v216, 0x46, v180
	v_cvt_pk_bf16_f32 v230, v179, v230
	s_nop 0
	s_nop 1
	v_cmp_le_i32_e32 vcc, v216, v169
	v_cmp_eq_u32_e64 s[100:101], v216, v169
	s_xnor_b64 vcc, vcc, s[38:39]
	s_andn2_b64 s[100:101], s[100:101], s[38:39]
	s_or_b64 vcc, vcc, s[100:101]
	v_cndmask_b32_e32 v231, 0, v233, vcc
	v_mul_f32_e32 v217, v231, v217
	v_cmp_eq_u32_e32 vcc, v216, v169
	v_mul_f32_e32 v231, v154, v217
	v_fma_f32 v217, v154, v217, v203
	s_and_b64 vcc, s[38:39], vcc
	v_cndmask_b32_e32 v231, v231, v217, vcc
	v_add_u32_e32 v217, 0x47, v180
	s_nop 1
	s_nop 1
	v_cmp_le_i32_e32 vcc, v217, v169
	v_cmp_eq_u32_e64 s[100:101], v217, v169
	s_xnor_b64 vcc, vcc, s[38:39]
	s_andn2_b64 s[100:101], s[100:101], s[38:39]
	s_or_b64 vcc, vcc, s[100:101]
	v_cndmask_b32_e32 v232, 0, v234, vcc
	v_mul_f32_e32 v218, v232, v218
	v_cmp_eq_u32_e32 vcc, v217, v169
	v_mul_f32_e32 v232, v155, v218
	v_fma_f32 v218, v155, v218, v203
	s_and_b64 vcc, s[38:39], vcc
	v_cndmask_b32_e32 v218, v232, v218, vcc
	v_cvt_pk_bf16_f32 v231, v231, v218
	v_add_u32_e32 v218, s5, v169
	v_ashrrev_i32_e32 v219, 31, v218
	v_mfma_f32_16x16x32_bf16 v[232:235], v[100:103], v[228:231], v[148:151]
	v_lshlrev_b64 v[218:219], 13, v[218:219]
	v_lshl_add_u64 v[218:219], v[198:199], 0, v[218:219]
	v_or_b32_e32 v169, 0x50, v176
	s_waitcnt vmcnt(5)
	v_mfma_f32_16x16x32_bf16 v[144:147], v[140:143], v[228:231], v[144:147]
	v_mov_b64_e32 v[150:151], s[94:95]
	s_nop 2
	v_pk_fma_f32 v[226:227], v[170:171], v[226:227], v[234:235] op_sel_hi:[0,1,1]
	v_pk_fma_f32 v[224:225], v[170:171], v[224:225], v[232:233] op_sel_hi:[0,1,1]
	v_cvt_pk_bf16_f32 v224, v224, v225
	v_cvt_pk_bf16_f32 v225, v226, v227
	v_pk_fma_f32 v[146:147], v[170:171], v[222:223], v[146:147] op_sel_hi:[0,1,1]
	v_pk_fma_f32 v[144:145], v[170:171], v[220:221], v[144:145] op_sel_hi:[0,1,1]
	v_cvt_pk_bf16_f32 v144, v144, v145
	v_cvt_pk_bf16_f32 v145, v146, v147
	global_store_dwordx2 v[218:219], v[224:225], off
	global_store_dwordx2 v[218:219], v[144:145], off offset:32
	v_lshlrev_b32_e32 v218, 8, v169
	v_mov_b64_e32 v[146:147], s[94:95]
	v_mov_b64_e32 v[148:149], s[92:93]
	v_add_u32_e32 v170, s87, v218
	s_and_b64 vcc, exec, s[46:47]
	v_mov_b64_e32 v[144:145], s[92:93]
	s_cbranch_vccz .LBB0_534
	s_and_b64 vcc, exec, s[46:47]
	s_cbranch_vccz .LBB0_535

; #define LAS __attribute__((address_space(3)))
; template <int MODE> __device__ __forceinline__ void ssd_scan_phase(Frame& F, int j, bool ctx_out) {
;     ...
; #pragma unroll
;                     for (int q = 0; q < 4; ++q) {
;                         const u32x2 lo = *(const LAS u32x2*)(CS + l * 256 + (((4 * q + (fq >> 1)) ^ fr) << 4) + (fq & 1) * 8), hi = *(const LAS u32x2*)(CS + l * 256 + (((4 * q + 2 + (fq >> 1)) ^ fr) << 4) + (fq & 1) * 8);
;                         u32x4 c4; c4.x = lo.x; c4.y = lo.y; c4.z = hi.x; c4.w = hi.y; const bf16x8 cfr = __builtin_bit_cast(bf16x8, c4);
;                         acco[0] = __builtin_amdgcn_mfma_f32_16x16x32_bf16(hf[0][q], cfr, acco[0], 0, 0, 0);
;                         acco[1] = __builtin_amdgcn_mfma_f32_16x16x32_bf16(hf[1][q], cfr, acco[1], 0, 0, 0);
;                     }
;                     {
;                         float gg[8]; unpack8(*(const LAS u32x4*)(GS + l * 256 + (((4 * kd + fq) ^ fr) << 4)), gg);
;                         const f32x4 ca = *(const LAS f32x4*)(tab + 32 * kd + 8 * fq), cb = *(const LAS f32x4*)(tab + 32 * kd + 8 * fq + 4);
;                         const f32x4 da = *(const LAS f32x4*)(tab + 128 + 32 * kd + 8 * fq), db = *(const LAS f32x4*)(tab + 128 + 32 * kd + 8 * fq + 4);
;                         const float cs[8] = {ca.x, ca.y, ca.z, ca.w, cb.x, cb.y, cb.z, cb.w}, ds[8] = {da.x, da.y, da.z, da.w, db.x, db.y, db.z, db.w};
;                         float m[8];
; #pragma unroll
;                         for (int jj = 0; jj < 8; ++jj) { const int s = 32 * kd + 8 * fq + jj; const bool valid = dir == 0 ? (s <= l) : (s >= l);
;                             const float e = valid ? __builtin_amdgcn_exp2f(cl - cs[jj]) : 0.f; m[jj] = gg[jj] * e * ds[jj]; if (dir == 0 && s == l) m[jj] += dsk; }
;                         const bf16x8 mf = __builtin_bit_cast(bf16x8, pack8(m));
;                         accd[0] = __builtin_amdgcn_mfma_f32_16x16x32_bf16(xa, mf, accd[0], 0, 0, 0);
;                         accd[1] = __builtin_amdgcn_mfma_f32_16x16x32_bf16(xb, mf, accd[1], 0, 0, 0);
;                     }
;                     const float el = __builtin_amdgcn_exp2f(cl);
; #pragma unroll
;                     for (int pt = 0; pt < 2; ++pt) { const f32x4 y = accd[pt] + acco[pt] * el; u32x2 o; o.x = cvt_pk_bf16(y[0], y[1]); o.y = cvt_pk_bf16(y[2], y[3]);
.LBB0_514:
	v_add3_u32 v178, 0, v218, v195
	v_add_u32_e32 v179, v178, v185
	ds_read_b64 v[218:219], v179
	v_add_u32_e32 v179, v178, v183
	ds_read_b64 v[220:221], v179
	v_add_u32_e32 v179, v178, v187
	ds_read_b64 v[226:227], v179
	v_add_u32_e32 v179, v178, v213
	ds_read_b64 v[228:229], v179
	s_waitcnt lgkmcnt(2)
	v_mfma_f32_16x16x32_bf16 v[222:225], v[116:119], v[218:221], 0
	v_add_u32_e32 v179, v178, v212
	ds_read_b64 v[230:231], v179
	v_add_u32_e32 v179, v178, v211
	v_mfma_f32_16x16x32_bf16 v[218:221], v[124:127], v[218:221], 0
	ds_read_b64 v[232:233], v179
	v_add_u32_e32 v179, v178, v191
	v_add_u32_e32 v178, v178, v210
	s_waitcnt lgkmcnt(2)
	v_mfma_f32_16x16x32_bf16 v[222:225], v[112:115], v[226:229], v[222:225]
	v_add_u32_e32 v170, v170, v168
	v_sub_f32_e32 v164, v171, v164
	v_exp_f32_e32 v164, v164
	v_mfma_f32_16x16x32_bf16 v[218:221], v[120:123], v[226:229], v[218:221]
	ds_read_b64 v[226:227], v179
	ds_read_b64 v[228:229], v178
	v_sub_f32_e32 v165, v171, v165
	s_waitcnt lgkmcnt(2)
	v_mfma_f32_16x16x32_bf16 v[222:225], v[108:111], v[230:233], v[222:225]
	v_exp_f32_e32 v165, v165
	v_sub_f32_e32 v166, v171, v166
	v_exp_f32_e32 v166, v166
	v_mfma_f32_16x16x32_bf16 v[218:221], v[128:131], v[230:233], v[218:221]
	ds_read_b128 v[230:233], v170
	v_add_u32_e32 v170, 64, v180
	s_waitcnt lgkmcnt(1)
	v_mfma_f32_16x16x32_bf16 v[222:225], v[104:107], v[226:229], v[222:225]
	s_waitcnt lgkmcnt(0)
	v_lshlrev_b32_e32 v178, 16, v230
	v_and_b32_e32 v179, 0xffff0000, v230
	v_lshlrev_b32_e32 v230, 16, v233
	v_mfma_f32_16x16x32_bf16 v[218:221], v[132:135], v[226:229], v[218:221]
	v_lshlrev_b32_e32 v226, 16, v231
	v_and_b32_e32 v227, 0xffff0000, v231
	v_lshlrev_b32_e32 v228, 16, v232
	v_and_b32_e32 v229, 0xffff0000, v232
	v_and_b32_e32 v231, 0xffff0000, v233
	v_cmp_le_i32_e32 vcc, v170, v169
	v_cmp_eq_u32_e64 s[100:101], v170, v169
	s_xnor_b64 vcc, vcc, s[38:39]
	s_andn2_b64 s[100:101], s[100:101], s[38:39]
	s_or_b64 vcc, vcc, s[100:101]
	v_sub_f32_e32 v156, v171, v156
	v_cndmask_b32_e32 v164, 0, v164, vcc
	v_mul_f32_e32 v164, v164, v178
	v_cmp_eq_u32_e32 vcc, v170, v169
	v_mul_f32_e32 v178, v160, v164
	s_and_b64 vcc, s[38:39], vcc
	v_fma_f32 v160, v160, v164, v203
	v_cndmask_b32_e32 v160, v178, v160, vcc
	v_cmp_le_i32_e32 vcc, v173, v169
	v_cmp_eq_u32_e64 s[100:101], v173, v169
	s_xnor_b64 vcc, vcc, s[38:39]
	s_andn2_b64 s[100:101], s[100:101], s[38:39]
	s_or_b64 vcc, vcc, s[100:101]
	v_exp_f32_e32 v156, v156
	v_sub_f32_e32 v157, v171, v157
	v_cndmask_b32_e32 v164, 0, v165, vcc
	v_mul_f32_e32 v164, v164, v179
	v_cmp_eq_u32_e32 vcc, v173, v169
	v_mul_f32_e32 v165, v161, v164
	s_and_b64 vcc, s[38:39], vcc
	v_fma_f32 v161, v161, v164, v203
	v_cndmask_b32_e32 v161, v165, v161, vcc
	v_cmp_le_i32_e32 vcc, v174, v169
	v_cmp_eq_u32_e64 s[100:101], v174, v169
	s_xnor_b64 vcc, vcc, s[38:39]
	s_andn2_b64 s[100:101], s[100:101], s[38:39]
	s_or_b64 vcc, vcc, s[100:101]
	v_exp_f32_e32 v157, v157
	v_sub_f32_e32 v158, v171, v158
	v_cndmask_b32_e32 v164, 0, v166, vcc
	v_mul_f32_e32 v164, v164, v226
	v_cmp_eq_u32_e32 vcc, v174, v169
	v_mul_f32_e32 v165, v162, v164
	s_and_b64 vcc, s[38:39], vcc
	v_fma_f32 v162, v162, v164, v203
	v_cndmask_b32_e32 v162, v165, v162, vcc
	v_sub_f32_e32 v166, v171, v167
	v_exp_f32_e32 v166, v166
	v_cmp_le_i32_e32 vcc, v175, v169
	v_cmp_eq_u32_e64 s[100:101], v175, v169
	s_xnor_b64 vcc, vcc, s[38:39]
	s_andn2_b64 s[100:101], s[100:101], s[38:39]
	s_or_b64 vcc, vcc, s[100:101]
	v_exp_f32_e32 v158, v158
	v_cndmask_b32_e32 v164, 0, v166, vcc
	v_mul_f32_e32 v164, v164, v227
	v_cmp_eq_u32_e32 vcc, v175, v169
	v_mul_f32_e32 v165, v163, v164
	s_and_b64 vcc, s[38:39], vcc
	v_fma_f32 v163, v163, v164, v203
	v_cndmask_b32_e32 v163, v165, v163, vcc
	v_cmp_le_i32_e32 vcc, v200, v169
	v_cmp_eq_u32_e64 s[100:101], v200, v169
	s_xnor_b64 vcc, vcc, s[38:39]
	s_andn2_b64 s[100:101], s[100:101], s[38:39]
	s_or_b64 vcc, vcc, s[100:101]
	s_mov_b32 s94, s92
	s_mov_b32 s95, s92
	v_cndmask_b32_e32 v156, 0, v156, vcc
	v_mul_f32_e32 v156, v156, v228
	v_cmp_eq_u32_e32 vcc, v200, v169
	v_mul_f32_e32 v164, v152, v156
	s_and_b64 vcc, s[38:39], vcc
	v_fma_f32 v152, v152, v156, v203
	v_cndmask_b32_e32 v156, v164, v152, vcc
	v_cmp_le_i32_e32 vcc, v201, v169
	v_cmp_eq_u32_e64 s[100:101], v201, v169
	s_xnor_b64 vcc, vcc, s[38:39]
	s_andn2_b64 s[100:101], s[100:101], s[38:39]
	s_or_b64 vcc, vcc, s[100:101]
	s_mov_b32 s93, s92
	s_nop 0
	v_cndmask_b32_e32 v152, 0, v157, vcc
	v_mul_f32_e32 v152, v152, v229
	v_cmp_eq_u32_e32 vcc, v201, v169
	v_mul_f32_e32 v157, v153, v152
	s_and_b64 vcc, s[38:39], vcc
	v_fma_f32 v152, v153, v152, v203
	v_cndmask_b32_e32 v157, v157, v152, vcc
	v_cmp_le_i32_e32 vcc, v216, v169
	v_cmp_eq_u32_e64 s[100:101], v216, v169
	s_xnor_b64 vcc, vcc, s[38:39]
	s_andn2_b64 s[100:101], s[100:101], s[38:39]
	s_or_b64 vcc, vcc, s[100:101]
	v_cndmask_b32_e32 v152, 0, v158, vcc
	v_mul_f32_e32 v152, v152, v230
	v_cmp_eq_u32_e32 vcc, v216, v169
	v_mul_f32_e32 v153, v154, v152
	s_and_b64 vcc, s[38:39], vcc
	v_fma_f32 v152, v154, v152, v203
	v_cndmask_b32_e32 v158, v153, v152, vcc
	v_sub_f32_e32 v154, v171, v159
	v_exp_f32_e32 v154, v154
	v_cmp_le_i32_e32 vcc, v217, v169
	v_cmp_eq_u32_e64 s[100:101], v217, v169
	s_xnor_b64 vcc, vcc, s[38:39]
	s_andn2_b64 s[100:101], s[100:101], s[38:39]
	s_or_b64 vcc, vcc, s[100:101]
	v_cndmask_b32_e32 v152, 0, v154, vcc
	v_mul_f32_e32 v152, v152, v231
	v_cmp_eq_u32_e32 vcc, v217, v169
	v_mul_f32_e32 v153, v155, v152
	s_and_b64 vcc, s[38:39], vcc
	v_fma_f32 v152, v155, v152, v203
	v_cndmask_b32_e32 v155, v153, v152, vcc
	v_cvt_pk_bf16_f32 v152, v160, v161
	v_cvt_pk_bf16_f32 v153, v162, v163
	v_cvt_pk_bf16_f32 v154, v156, v157
	v_cvt_pk_bf16_f32 v155, v158, v155
	ds_read_b32 v161, v214 offset:384
	v_or_b32_e32 v160, 0x60, v176
	v_mfma_f32_16x16x32_bf16 v[144:147], v[100:103], v[152:155], v[144:147]
	v_mov_b64_e32 v[102:103], s[94:95]
	v_mov_b64_e32 v[100:101], s[92:93]
	s_and_b64 vcc, exec, s[46:47]
	v_mfma_f32_16x16x32_bf16 v[140:143], v[140:143], v[152:155], v[148:151]
	s_nop 2
	v_exp_f32_e32 v148, v171
	v_add_u32_e32 v150, s5, v169
	v_ashrrev_i32_e32 v151, 31, v150
	v_lshlrev_b64 v[150:151], 13, v[150:151]
	v_pk_fma_f32 v[146:147], v[148:149], v[224:225], v[146:147] op_sel_hi:[0,1,1]
	v_pk_fma_f32 v[144:145], v[148:149], v[222:223], v[144:145] op_sel_hi:[0,1,1]
	v_pk_fma_f32 v[142:143], v[148:149], v[220:221], v[142:143] op_sel_hi:[0,1,1]
	v_pk_fma_f32 v[140:141], v[148:149], v[218:219], v[140:141] op_sel_hi:[0,1,1]
	v_lshl_add_u64 v[150:151], v[198:199], 0, v[150:151]
	v_cvt_pk_bf16_f32 v144, v144, v145
	v_cvt_pk_bf16_f32 v145, v146, v147
	v_cvt_pk_bf16_f32 v140, v140, v141
	v_cvt_pk_bf16_f32 v141, v142, v143
	global_store_dwordx2 v[150:151], v[144:145], off
	global_store_dwordx2 v[150:151], v[140:141], off offset:32
	v_lshlrev_b32_e32 v141, 8, v160
	v_mov_b64_e32 v[150:151], s[94:95]
	v_add_u32_e32 v140, s87, v141
	v_mov_b64_e32 v[148:149], s[92:93]
	s_cbranch_vccz .LBB0_536
	s_and_b64 vcc, exec, s[46:47]
	s_cbranch_vccz .LBB0_537

; #define LAS __attribute__((address_space(3)))
; template <int MODE> __device__ __forceinline__ void ssd_scan_phase(Frame& F, int j, bool ctx_out) {
;     ...
; #pragma unroll
;                     for (int q = 0; q < 4; ++q) {
;                         const u32x2 lo = *(const LAS u32x2*)(CS + l * 256 + (((4 * q + (fq >> 1)) ^ fr) << 4) + (fq & 1) * 8), hi = *(const LAS u32x2*)(CS + l * 256 + (((4 * q + 2 + (fq >> 1)) ^ fr) << 4) + (fq & 1) * 8);
;                         u32x4 c4; c4.x = lo.x; c4.y = lo.y; c4.z = hi.x; c4.w = hi.y; const bf16x8 cfr = __builtin_bit_cast(bf16x8, c4);
;                         acco[0] = __builtin_amdgcn_mfma_f32_16x16x32_bf16(hf[0][q], cfr, acco[0], 0, 0, 0);
;                         acco[1] = __builtin_amdgcn_mfma_f32_16x16x32_bf16(hf[1][q], cfr, acco[1], 0, 0, 0);
;                     }
;                     {
;                         float gg[8]; unpack8(*(const LAS u32x4*)(GS + l * 256 + (((4 * kd + fq) ^ fr) << 4)), gg);
;                         const f32x4 ca = *(const LAS f32x4*)(tab + 32 * kd + 8 * fq), cb = *(const LAS f32x4*)(tab + 32 * kd + 8 * fq + 4);
;                         const f32x4 da = *(const LAS f32x4*)(tab + 128 + 32 * kd + 8 * fq), db = *(const LAS f32x4*)(tab + 128 + 32 * kd + 8 * fq + 4);
;                         const float cs[8] = {ca.x, ca.y, ca.z, ca.w, cb.x, cb.y, cb.z, cb.w}, ds[8] = {da.x, da.y, da.z, da.w, db.x, db.y, db.z, db.w};
;                         float m[8];
; #pragma unroll
;                         for (int jj = 0; jj < 8; ++jj) { const int s = 32 * kd + 8 * fq + jj; const bool valid = dir == 0 ? (s <= l) : (s >= l);
;                             const float e = valid ? __builtin_amdgcn_exp2f(cl - cs[jj]) : 0.f; m[jj] = gg[jj] * e * ds[jj]; if (dir == 0 && s == l) m[jj] += dsk; }
.LBB0_518:
	v_add3_u32 v141, 0, v141, v195
	v_add_u32_e32 v142, v141, v185
	v_add_u32_e32 v144, v141, v183
	ds_read_b64 v[142:143], v142
	ds_read_b64 v[144:145], v144
	v_add_u32_e32 v146, v141, v187
	ds_read_b64 v[152:153], v146
	ds_read_b32 v162, v214 offset:448
	v_add_u32_e32 v146, v141, v213
	ds_read_b64 v[154:155], v146
	s_waitcnt lgkmcnt(3)
	v_mfma_f32_16x16x32_bf16 v[156:159], v[116:119], v[142:145], 0
	v_add_u32_e32 v146, v141, v212
	v_add_u32_e32 v147, v141, v211
	v_add_u32_e32 v163, v141, v191
	v_mfma_f32_16x16x32_bf16 v[142:145], v[124:127], v[142:145], 0
	ds_read_b64 v[164:165], v146
	ds_read_b64 v[166:167], v147
	ds_read_b64 v[216:217], v163
	v_add_u32_e32 v141, v141, v210
	v_lshlrev_b32_e32 v171, 4, v205
	s_waitcnt lgkmcnt(3)
	v_mfma_f32_16x16x32_bf16 v[156:159], v[112:115], v[152:155], v[156:159]
	ds_read_b64 v[218:219], v141
	v_add_u32_e32 v140, v140, v171
	v_add_u32_e32 v170, 0x61, v180
	v_mfma_f32_16x16x32_bf16 v[142:145], v[120:123], v[152:155], v[142:145]
	v_add_u32_e32 v169, 0x62, v180
	s_mov_b32 s94, s92
	s_waitcnt lgkmcnt(2)
	v_mfma_f32_16x16x32_bf16 v[152:155], v[108:111], v[164:167], v[156:159]
	s_mov_b32 s95, s92
	s_mov_b32 s93, s92
	s_nop 0
	ds_read_b128 v[156:159], v197 offset:384
	v_mfma_f32_16x16x32_bf16 v[142:145], v[128:131], v[164:167], v[142:145]
	ds_read_b128 v[164:167], v140
	s_waitcnt lgkmcnt(1)
	v_sub_f32_e32 v140, v161, v156
	v_mfma_f32_16x16x32_bf16 v[220:223], v[104:107], v[216:219], v[152:155]
	s_waitcnt lgkmcnt(0)
	v_lshlrev_b32_e32 v174, 16, v166
	v_and_b32_e32 v175, 0xffff0000, v166
	v_exp_f32_e32 v166, v140
	v_mfma_f32_16x16x32_bf16 v[216:219], v[132:135], v[216:219], v[142:145]
	ds_read_b128 v[152:155], v197 offset:896
	v_lshlrev_b32_e32 v163, 16, v164
	v_cndmask_b32_e64 v166, 0, v166, s[40:41]
	ds_read_b128 v[144:147], v197 offset:400
	v_mul_f32_e32 v163, v166, v163
	s_waitcnt lgkmcnt(1)
	v_mul_f32_e32 v166, v152, v163
	v_fma_f32 v163, v152, v163, v203
	v_lshlrev_b32_e32 v178, 16, v167
	v_and_b32_e32 v179, 0xffff0000, v167
	ds_read_b128 v[140:143], v197 offset:912
	v_cndmask_b32_e64 v197, v166, v163, s[42:43]
	v_sub_f32_e32 v167, v161, v157
	v_exp_f32_e32 v167, v167
	v_cmp_le_i32_e32 vcc, v170, v160
	v_cmp_eq_u32_e64 s[100:101], v170, v160
	s_xnor_b64 vcc, vcc, s[38:39]
	s_andn2_b64 s[100:101], s[100:101], s[38:39]
	s_or_b64 vcc, vcc, s[100:101]
	v_and_b32_e32 v164, 0xffff0000, v164
	v_sub_f32_e32 v166, v161, v158
	v_cndmask_b32_e32 v163, 0, v167, vcc
	v_mul_f32_e32 v163, v163, v164
	v_cmp_eq_u32_e32 vcc, v170, v160
	v_mul_f32_e32 v164, v153, v163
	v_fma_f32 v163, v153, v163, v203
	s_and_b64 vcc, s[38:39], vcc
	v_cndmask_b32_e32 v200, v164, v163, vcc
	v_exp_f32_e32 v166, v166
	v_lshlrev_b32_e32 v173, 16, v165
	v_add_u32_e32 v167, 0x63, v180
	v_and_b32_e32 v165, 0xffff0000, v165
	v_cmp_le_i32_e32 vcc, v169, v160
	v_cmp_eq_u32_e64 s[100:101], v169, v160
	s_xnor_b64 vcc, vcc, s[38:39]
	s_andn2_b64 s[100:101], s[100:101], s[38:39]
	s_or_b64 vcc, vcc, s[100:101]
	s_waitcnt lgkmcnt(1)
	v_sub_f32_e32 v214, v161, v145
	v_exp_f32_e32 v214, v214
	v_cndmask_b32_e32 v163, 0, v166, vcc
	v_mul_f32_e32 v163, v163, v173
	v_cmp_eq_u32_e32 vcc, v169, v160
	v_mul_f32_e32 v164, v154, v163
	v_fma_f32 v163, v154, v163, v203
	s_and_b64 vcc, s[38:39], vcc
	v_cndmask_b32_e32 v173, v164, v163, vcc
	v_sub_f32_e32 v166, v161, v159
	v_exp_f32_e32 v166, v166
	v_sub_f32_e32 v224, v161, v146
	v_exp_f32_e32 v224, v224
	v_cmp_le_i32_e32 vcc, v167, v160
	v_cmp_eq_u32_e64 s[100:101], v167, v160
	s_xnor_b64 vcc, vcc, s[38:39]
	s_andn2_b64 s[100:101], s[100:101], s[38:39]
	s_or_b64 vcc, vcc, s[100:101]
	v_sub_f32_e32 v225, v161, v147
	v_exp_f32_e32 v225, v225
	v_cndmask_b32_e32 v163, 0, v166, vcc
	v_mul_f32_e32 v163, v163, v165
	v_cmp_eq_u32_e32 vcc, v167, v160
	v_mul_f32_e32 v164, v155, v163
	v_fma_f32 v163, v155, v163, v203
	s_and_b64 vcc, s[38:39], vcc
	v_add_u32_e32 v166, 0x64, v180
	v_cndmask_b32_e32 v201, v164, v163, vcc
	v_sub_f32_e32 v165, v161, v144
	v_exp_f32_e32 v165, v165
	s_nop 1
	v_cmp_le_i32_e32 vcc, v166, v160
	v_cmp_eq_u32_e64 s[100:101], v166, v160
	s_xnor_b64 vcc, vcc, s[38:39]
	s_andn2_b64 s[100:101], s[100:101], s[38:39]
	s_or_b64 vcc, vcc, s[100:101]
	v_cndmask_b32_e32 v163, 0, v165, vcc
	v_mul_f32_e32 v163, v163, v174
	v_cmp_eq_u32_e32 vcc, v166, v160
	s_waitcnt lgkmcnt(0)
; __device__ __forceinline__ unsigned cvt_pk_bf16(float lo, float hi) { const f32x2 v = {lo, hi}; return __builtin_bit_cast(unsigned, __builtin_convertvector(v, bf16x2_t)); }
; __device__ __forceinline__ u32x4 pack8(const float (&f)[8]) { u32x4 w; w.x = cvt_pk_bf16(f[0], f[1]); w.y = cvt_pk_bf16(f[2], f[3]); w.z = cvt_pk_bf16(f[4], f[5]); w.w = cvt_pk_bf16(f[6], f[7]); return w; }
; template <int MODE> __device__ __forceinline__ void ssd_scan_phase(Frame& F, int j, bool ctx_out) {
;     ...
;                         for (int jj = 0; jj < 8; ++jj) { const int s = 32 * kd + 8 * fq + jj; const bool valid = dir == 0 ? (s <= l) : (s >= l);
;                             const float e = valid ? __builtin_amdgcn_exp2f(cl - cs[jj]) : 0.f; m[jj] = gg[jj] * e * ds[jj]; if (dir == 0 && s == l) m[jj] += dsk; }
;                         const bf16x8 mf = __builtin_bit_cast(bf16x8, pack8(m));
;                         accd[0] = __builtin_amdgcn_mfma_f32_16x16x32_bf16(xa, mf, accd[0], 0, 0, 0);
;                         accd[1] = __builtin_amdgcn_mfma_f32_16x16x32_bf16(xb, mf, accd[1], 0, 0, 0);
;                     }
;                     const float el = __builtin_amdgcn_exp2f(cl);
; #pragma unroll
;                     for (int pt = 0; pt < 2; ++pt) { const f32x4 y = accd[pt] + acco[pt] * el; u32x2 o; o.x = cvt_pk_bf16(y[0], y[1]); o.y = cvt_pk_bf16(y[2], y[3]);
;                         *(u32x2*)(yout + (size_t)(row0 + l) * DI + h * 64 + ph * 32 + 16 * pt + 4 * fq) = o; }
	v_mul_f32_e32 v164, v140, v163
	v_fma_f32 v163, v140, v163, v203
	s_and_b64 vcc, s[38:39], vcc
	v_add_u32_e32 v165, 0x65, v180
	v_cndmask_b32_e32 v174, v164, v163, vcc
	s_nop 1
	s_nop 1
	v_cmp_le_i32_e32 vcc, v165, v160
	v_cmp_eq_u32_e64 s[100:101], v165, v160
	s_xnor_b64 vcc, vcc, s[38:39]
	s_andn2_b64 s[100:101], s[100:101], s[38:39]
	s_or_b64 vcc, vcc, s[100:101]
	v_cndmask_b32_e32 v163, 0, v214, vcc
	v_mul_f32_e32 v163, v163, v175
	v_cmp_eq_u32_e32 vcc, v165, v160
	v_mul_f32_e32 v164, v141, v163
	v_fma_f32 v163, v141, v163, v203
	s_and_b64 vcc, s[38:39], vcc
	v_cndmask_b32_e32 v175, v164, v163, vcc
	v_add_u32_e32 v164, 0x66, v180
	v_cvt_pk_bf16_f32 v226, v174, v175
	v_exp_f32_e32 v174, v161
	s_nop 1
	v_cmp_le_i32_e32 vcc, v164, v160
	v_cmp_eq_u32_e64 s[100:101], v164, v160
	s_xnor_b64 vcc, vcc, s[38:39]
	s_andn2_b64 s[100:101], s[100:101], s[38:39]
	s_or_b64 vcc, vcc, s[100:101]
	v_cndmask_b32_e32 v163, 0, v224, vcc
	v_mul_f32_e32 v163, v163, v178
	v_cmp_eq_u32_e32 vcc, v164, v160
	v_mul_f32_e32 v178, v142, v163
	v_fma_f32 v163, v142, v163, v203
	s_and_b64 vcc, s[38:39], vcc
	v_cndmask_b32_e32 v178, v178, v163, vcc
	v_add_u32_e32 v163, 0x67, v180
	s_nop 1
	s_nop 1
	v_cmp_le_i32_e32 vcc, v163, v160
	v_cmp_eq_u32_e64 s[100:101], v163, v160
	s_xnor_b64 vcc, vcc, s[38:39]
	s_andn2_b64 s[100:101], s[100:101], s[38:39]
	s_or_b64 vcc, vcc, s[100:101]
	v_cvt_pk_bf16_f32 v224, v197, v200
	s_nop 0
	v_cndmask_b32_e32 v214, 0, v225, vcc
	v_mul_f32_e32 v179, v214, v179
	v_cmp_eq_u32_e32 vcc, v163, v160
	v_mul_f32_e32 v214, v143, v179
	v_fma_f32 v179, v143, v179, v203
	s_and_b64 vcc, s[38:39], vcc
	v_cndmask_b32_e32 v179, v214, v179, vcc
	v_cvt_pk_bf16_f32 v225, v173, v201
	v_cvt_pk_bf16_f32 v227, v178, v179
	v_add_u32_e32 v160, s5, v160
	v_ashrrev_i32_e32 v161, 31, v160
	v_mfma_f32_16x16x32_bf16 v[228:231], v[8:11], v[224:227], v[148:151]
	v_lshlrev_b64 v[160:161], 13, v[160:161]
	v_lshl_add_u64 v[160:161], v[198:199], 0, v[160:161]
	s_and_b64 vcc, exec, s[46:47]
	s_waitcnt vmcnt(4)
	v_mfma_f32_16x16x32_bf16 v[100:103], v[136:139], v[224:227], v[100:103]
	v_mov_b64_e32 v[150:151], s[94:95]
	s_nop 1
	v_pk_fma_f32 v[200:201], v[174:175], v[222:223], v[230:231] op_sel_hi:[0,1,1]
	v_pk_fma_f32 v[220:221], v[174:175], v[220:221], v[228:229] op_sel_hi:[0,1,1]
	v_cvt_pk_bf16_f32 v220, v220, v221
	v_cvt_pk_bf16_f32 v221, v200, v201
	s_nop 0
	v_pk_fma_f32 v[102:103], v[174:175], v[218:219], v[102:103] op_sel_hi:[0,1,1]
	v_pk_fma_f32 v[100:101], v[174:175], v[216:217], v[100:101] op_sel_hi:[0,1,1]
	v_cvt_pk_bf16_f32 v100, v100, v101
	v_cvt_pk_bf16_f32 v101, v102, v103
	global_store_dwordx2 v[160:161], v[220:221], off
	global_store_dwordx2 v[160:161], v[100:101], off offset:32
	v_or_b32_e32 v160, 0x70, v176
	v_lshlrev_b32_e32 v173, 8, v160
	v_mov_b64_e32 v[102:103], s[94:95]
	v_mov_b64_e32 v[148:149], s[92:93]
	v_add_u32_e32 v161, s87, v173
	v_mov_b64_e32 v[100:101], s[92:93]
	s_cbranch_vccz .LBB0_538
	s_and_b64 vcc, exec, s[46:47]
	s_cbranch_vccz .LBB0_539

; #define LAS __attribute__((address_space(3)))
; template <int MODE> __device__ __forceinline__ void ssd_scan_phase(Frame& F, int j, bool ctx_out) {
;     ...
; #pragma unroll
;                     for (int q = 0; q < 4; ++q) {
;                         const u32x2 lo = *(const LAS u32x2*)(CS + l * 256 + (((4 * q + (fq >> 1)) ^ fr) << 4) + (fq & 1) * 8), hi = *(const LAS u32x2*)(CS + l * 256 + (((4 * q + 2 + (fq >> 1)) ^ fr) << 4) + (fq & 1) * 8);
;                         u32x4 c4; c4.x = lo.x; c4.y = lo.y; c4.z = hi.x; c4.w = hi.y; const bf16x8 cfr = __builtin_bit_cast(bf16x8, c4);
;                         acco[0] = __builtin_amdgcn_mfma_f32_16x16x32_bf16(hf[0][q], cfr, acco[0], 0, 0, 0);
;                         acco[1] = __builtin_amdgcn_mfma_f32_16x16x32_bf16(hf[1][q], cfr, acco[1], 0, 0, 0);
;                     }
;                     {
;                         float gg[8]; unpack8(*(const LAS u32x4*)(GS + l * 256 + (((4 * kd + fq) ^ fr) << 4)), gg);
;                         const f32x4 ca = *(const LAS f32x4*)(tab + 32 * kd + 8 * fq), cb = *(const LAS f32x4*)(tab + 32 * kd + 8 * fq + 4);
;                         const f32x4 da = *(const LAS f32x4*)(tab + 128 + 32 * kd + 8 * fq), db = *(const LAS f32x4*)(tab + 128 + 32 * kd + 8 * fq + 4);
;                         const float cs[8] = {ca.x, ca.y, ca.z, ca.w, cb.x, cb.y, cb.z, cb.w}, ds[8] = {da.x, da.y, da.z, da.w, db.x, db.y, db.z, db.w};
;                         float m[8];
; #pragma unroll
;                         for (int jj = 0; jj < 8; ++jj) { const int s = 32 * kd + 8 * fq + jj; const bool valid = dir == 0 ? (s <= l) : (s >= l);
;                             const float e = valid ? __builtin_amdgcn_exp2f(cl - cs[jj]) : 0.f; m[jj] = gg[jj] * e * ds[jj]; if (dir == 0 && s == l) m[jj] += dsk; }
;                         const bf16x8 mf = __builtin_bit_cast(bf16x8, pack8(m));
;                         accd[0] = __builtin_amdgcn_mfma_f32_16x16x32_bf16(xa, mf, accd[0], 0, 0, 0);
;                         accd[1] = __builtin_amdgcn_mfma_f32_16x16x32_bf16(xb, mf, accd[1], 0, 0, 0);
;                     }
;                     const float el = __builtin_amdgcn_exp2f(cl);
; #pragma unroll
;                     for (int pt = 0; pt < 2; ++pt) { const f32x4 y = accd[pt] + acco[pt] * el; u32x2 o; o.x = cvt_pk_bf16(y[0], y[1]); o.y = cvt_pk_bf16(y[2], y[3]);
.LBB0_522:
	v_add3_u32 v168, 0, v173, v195
	v_add_u32_e32 v172, v168, v185
	v_add_u32_e32 v174, v168, v183
	ds_read_b64 v[172:173], v172
	ds_read_b64 v[174:175], v174
	v_add_u32_e32 v178, v168, v187
	s_waitcnt lgkmcnt(0)
	v_mfma_f32_16x16x32_bf16 v[116:119], v[116:119], v[172:175], 0
	v_mfma_f32_16x16x32_bf16 v[124:127], v[124:127], v[172:175], 0
	v_add_u32_e32 v174, v168, v213
	ds_read_b64 v[172:173], v178
	ds_read_b64 v[174:175], v174
	s_waitcnt lgkmcnt(0)
	v_mfma_f32_16x16x32_bf16 v[112:115], v[112:115], v[172:175], v[116:119]
	s_nop 2
	v_add_u32_e32 v116, v168, v212
	v_add_u32_e32 v118, v168, v211
	ds_read_b64 v[116:117], v116
	ds_read_b64 v[118:119], v118
	v_mfma_f32_16x16x32_bf16 v[120:123], v[120:123], v[172:175], v[124:127]
	s_nop 2
	v_add_u32_e32 v124, v168, v191
	s_waitcnt lgkmcnt(0)
	v_mfma_f32_16x16x32_bf16 v[108:111], v[108:111], v[116:119], v[112:115]
	s_nop 2
	v_add_u32_e32 v114, v168, v210
	ds_read_b64 v[112:113], v124
	ds_read_b64 v[114:115], v114
	v_mfma_f32_16x16x32_bf16 v[116:119], v[128:131], v[116:119], v[120:123]
	v_add_u32_e32 v124, 0x60, v180
	v_add_u32_e32 v120, v161, v171
	ds_read_b128 v[120:123], v120
	s_waitcnt lgkmcnt(1)
	v_mfma_f32_16x16x32_bf16 v[108:111], v[104:107], v[112:115], v[108:111]
	s_waitcnt lgkmcnt(0)
	v_lshlrev_b32_e32 v125, 16, v120
	v_mfma_f32_16x16x32_bf16 v[104:107], v[132:135], v[112:115], v[116:119]
	v_lshlrev_b32_e32 v126, 16, v121
	v_and_b32_e32 v112, 0xffff0000, v121
	v_sub_f32_e32 v121, v162, v157
	v_sub_f32_e32 v119, v162, v156
	v_exp_f32_e32 v119, v119
	v_cmp_le_i32_e32 vcc, v124, v160
	v_cmp_eq_u32_e64 s[100:101], v124, v160
	s_xnor_b64 vcc, vcc, s[38:39]
	s_andn2_b64 s[100:101], s[100:101], s[38:39]
	s_or_b64 vcc, vcc, s[100:101]
	v_exp_f32_e32 v121, v121
	v_cndmask_b32_e32 v117, 0, v119, vcc
	v_mul_f32_e32 v117, v117, v125
	v_cmp_eq_u32_e32 vcc, v124, v160
	v_mul_f32_e32 v118, v152, v117
	s_and_b64 vcc, s[38:39], vcc
	v_fma_f32 v117, v152, v117, v203
	v_cndmask_b32_e32 v117, v118, v117, vcc
	v_and_b32_e32 v120, 0xffff0000, v120
	v_cmp_le_i32_e32 vcc, v170, v160
	v_cmp_eq_u32_e64 s[100:101], v170, v160
	s_xnor_b64 vcc, vcc, s[38:39]
	s_andn2_b64 s[100:101], s[100:101], s[38:39]
	s_or_b64 vcc, vcc, s[100:101]
	v_lshlrev_b32_e32 v113, 16, v122
	v_cndmask_b32_e32 v118, 0, v121, vcc
	v_mul_f32_e32 v118, v118, v120
	v_cmp_eq_u32_e32 vcc, v170, v160
	v_mul_f32_e32 v119, v153, v118
	s_and_b64 vcc, s[38:39], vcc
	v_fma_f32 v118, v153, v118, v203
	v_cndmask_b32_e32 v118, v119, v118, vcc
	v_sub_f32_e32 v121, v162, v158
	v_exp_f32_e32 v121, v121
	v_cmp_le_i32_e32 vcc, v169, v160
	v_cmp_eq_u32_e64 s[100:101], v169, v160
	s_xnor_b64 vcc, vcc, s[38:39]
	s_andn2_b64 s[100:101], s[100:101], s[38:39]
	s_or_b64 vcc, vcc, s[100:101]
	v_and_b32_e32 v114, 0xffff0000, v122
	v_cndmask_b32_e32 v119, 0, v121, vcc
	v_mul_f32_e32 v119, v119, v126
	v_cmp_eq_u32_e32 vcc, v169, v160
	v_mul_f32_e32 v120, v154, v119
	s_and_b64 vcc, s[38:39], vcc
	v_fma_f32 v119, v154, v119, v203
	v_cndmask_b32_e32 v119, v120, v119, vcc
	v_sub_f32_e32 v122, v162, v159
	v_exp_f32_e32 v122, v122
	v_cmp_le_i32_e32 vcc, v167, v160
	v_cmp_eq_u32_e64 s[100:101], v167, v160
	s_xnor_b64 vcc, vcc, s[38:39]
	s_andn2_b64 s[100:101], s[100:101], s[38:39]
	s_or_b64 vcc, vcc, s[100:101]
	v_lshlrev_b32_e32 v115, 16, v123
	v_cndmask_b32_e32 v120, 0, v122, vcc
	v_mul_f32_e32 v112, v120, v112
	v_cmp_eq_u32_e32 vcc, v167, v160
	v_mul_f32_e32 v120, v155, v112
	s_and_b64 vcc, s[38:39], vcc
	v_fma_f32 v112, v155, v112, v203
	v_cndmask_b32_e32 v120, v120, v112, vcc
	v_sub_f32_e32 v122, v162, v144
	v_exp_f32_e32 v122, v122
	v_cmp_le_i32_e32 vcc, v166, v160
	v_cmp_eq_u32_e64 s[100:101], v166, v160
	s_xnor_b64 vcc, vcc, s[38:39]
	s_andn2_b64 s[100:101], s[100:101], s[38:39]
	s_or_b64 vcc, vcc, s[100:101]
	v_and_b32_e32 v116, 0xffff0000, v123
	v_cndmask_b32_e32 v112, 0, v122, vcc
	v_mul_f32_e32 v112, v112, v113
	v_cmp_eq_u32_e32 vcc, v166, v160
	v_mul_f32_e32 v113, v140, v112
	s_and_b64 vcc, s[38:39], vcc
	v_fma_f32 v112, v140, v112, v203
	v_cndmask_b32_e32 v121, v113, v112, vcc
	v_sub_f32_e32 v122, v162, v145
	v_exp_f32_e32 v122, v122
	v_cmp_le_i32_e32 vcc, v165, v160
	v_cmp_eq_u32_e64 s[100:101], v165, v160
	s_xnor_b64 vcc, vcc, s[38:39]
	s_andn2_b64 s[100:101], s[100:101], s[38:39]
	s_or_b64 vcc, vcc, s[100:101]
	s_nop 0
	v_cndmask_b32_e32 v112, 0, v122, vcc
	v_mul_f32_e32 v112, v112, v114
	v_cmp_eq_u32_e32 vcc, v165, v160
	v_mul_f32_e32 v113, v141, v112
	s_and_b64 vcc, s[38:39], vcc
	v_fma_f32 v112, v141, v112, v203
	v_cndmask_b32_e32 v114, v113, v112, vcc
	v_sub_f32_e32 v122, v162, v146
	v_exp_f32_e32 v122, v122
	v_cmp_le_i32_e32 vcc, v164, v160
	v_cmp_eq_u32_e64 s[100:101], v164, v160
	s_xnor_b64 vcc, vcc, s[38:39]
	s_andn2_b64 s[100:101], s[100:101], s[38:39]
	s_or_b64 vcc, vcc, s[100:101]
	v_cvt_pk_bf16_f32 v114, v121, v114
	v_cndmask_b32_e32 v112, 0, v122, vcc
	v_mul_f32_e32 v112, v112, v115
	v_cmp_eq_u32_e32 vcc, v164, v160
	v_mul_f32_e32 v113, v142, v112
	s_and_b64 vcc, s[38:39], vcc
	v_fma_f32 v112, v142, v112, v203
	v_cndmask_b32_e32 v115, v113, v112, vcc
	v_sub_f32_e32 v122, v162, v147
	v_exp_f32_e32 v122, v122
	v_cmp_le_i32_e32 vcc, v163, v160
	v_cmp_eq_u32_e64 s[100:101], v163, v160
	s_xnor_b64 vcc, vcc, s[38:39]
	s_andn2_b64 s[100:101], s[100:101], s[38:39]
	s_or_b64 vcc, vcc, s[100:101]
	v_cndmask_b32_e32 v112, 0, v122, vcc
	v_mul_f32_e32 v112, v112, v116
	v_cmp_eq_u32_e32 vcc, v163, v160
	v_mul_f32_e32 v113, v143, v112
	s_and_b64 vcc, s[38:39], vcc
	v_fma_f32 v112, v143, v112, v203
	v_cndmask_b32_e32 v116, v113, v112, vcc
	v_cvt_pk_bf16_f32 v112, v117, v118
	v_cvt_pk_bf16_f32 v113, v119, v120
	v_cvt_pk_bf16_f32 v115, v115, v116
	s_nop 1
	v_mfma_f32_16x16x32_bf16 v[8:11], v[8:11], v[112:115], v[100:103]
	v_mfma_f32_16x16x32_bf16 v[100:103], v[136:139], v[112:115], v[148:151]
	v_exp_f32_e32 v112, v162
	v_add_u32_e32 v114, s5, v160
	v_ashrrev_i32_e32 v115, 31, v114
	v_lshlrev_b64 v[114:115], 13, v[114:115]
	s_nop 2
	v_pk_fma_f32 v[10:11], v[112:113], v[110:111], v[10:11] op_sel_hi:[0,1,1]
	v_pk_fma_f32 v[8:9], v[112:113], v[108:109], v[8:9] op_sel_hi:[0,1,1]
	v_lshl_add_u64 v[114:115], v[198:199], 0, v[114:115]
	v_cvt_pk_bf16_f32 v8, v8, v9
	v_cvt_pk_bf16_f32 v9, v10, v11
	global_store_dwordx2 v[114:115], v[8:9], off
	v_pk_fma_f32 v[8:9], v[112:113], v[106:107], v[102:103] op_sel_hi:[0,1,1]
	v_pk_fma_f32 v[10:11], v[112:113], v[104:105], v[100:101] op_sel_hi:[0,1,1]
	v_cvt_pk_bf16_f32 v10, v10, v11
	v_cvt_pk_bf16_f32 v11, v8, v9
	global_store_dwordx2 v[114:115], v[10:11], off offset:32
	s_branch .Lscan_b4_y
